# speedup vs baseline: 1.0143x; 1.0143x over previous
; __device__ __forceinline__ float silu_f(float x) { return x * __builtin_amdgcn_rcpf(1.f + __expf(-x)); }
;   __device__ __forceinline__ void operator()(int brow, int bcol, int wr, int wc, int fr, int fq, f32x4 (&acc)[4][4], int split) const {
;     if (rowss && brow < TL) norm_fix(acc, rowss, shW, NGU, brow, bcol, wr, wc, fr, fq);
; #pragma unroll
;     for (int m = 0; m < 4; m++)
; #pragma unroll
;       for (int pr = 0; pr < 2; pr++)
; #pragma unroll
;         for (int j = 0; j < 4; j++) {
;           int row = brow + wr * 64 + m * 16 + fq * 4 + j;
;           int col = (bcol >> 1) + wc * 32 + pr * 16 + fr;
;           float g = acc[m][2 * pr][j], u = acc[m][2 * pr + 1][j];
;           act[(size_t)row * DFF + col] = f2bf(silu_f(g) * u);
;         }
;   }
.LBB0_190:
	v_mul_f32_e32 v152, 0xbfb8aa3b, v120
	v_exp_f32_e32 v152, v152
	s_ashr_i32 s31, s42, 1
	v_add_u32_e32 v136, s31, v140
	v_ashrrev_i32_e32 v137, 31, v136
	v_add_f32_e32 v152, 1.0, v152
	v_rcp_f32_e32 v152, v152
	v_add_u32_e32 v151, s44, v141
	v_lshl_add_u64 v[136:137], v[136:137], 1, s[82:83]
	v_add_u32_e32 v154, 16, v151
	v_mul_f32_e32 v120, v120, v152
	v_mul_f32_e32 v120, v124, v120
	v_mul_f32_e32 v124, 0xbfb8aa3b, v121
	v_exp_f32_e32 v124, v124
	v_cvt_pk_bf16_f32 v120, v120, s0
	v_mad_i64_i32 v[152:153], s[42:43], v151, s56, v[136:137]
	v_add_f32_e32 v124, 1.0, v124
	v_rcp_f32_e32 v124, v124
	global_store_short v[152:153], v120, off
	v_add_u32_e32 v120, 1, v151
	v_add_u32_e32 v155, 17, v151
	v_mul_f32_e32 v121, v121, v124
	v_mul_f32_e32 v121, v125, v121
	v_mul_f32_e32 v125, 0xbfb8aa3b, v122
	v_exp_f32_e32 v125, v125
	v_cvt_pk_bf16_f32 v124, v121, s0
	v_mad_i64_i32 v[120:121], s[42:43], v120, s56, v[136:137]
	v_add_f32_e32 v125, 1.0, v125
	v_rcp_f32_e32 v125, v125
	global_store_short v[120:121], v124, off
	v_add_u32_e32 v124, 2, v151
	v_add_u32_e32 v156, 18, v151
	v_mul_f32_e32 v122, v122, v125
	v_mul_f32_e32 v122, v126, v122
	v_mul_f32_e32 v126, 0xbfb8aa3b, v123
	v_exp_f32_e32 v126, v126
	v_cvt_pk_bf16_f32 v122, v122, s0
	v_mad_i64_i32 v[124:125], s[42:43], v124, s56, v[136:137]
	v_add_f32_e32 v126, 1.0, v126
	v_rcp_f32_e32 v126, v126
	global_store_short v[124:125], v122, off
	v_add_u32_e32 v122, 3, v151
	v_add_u32_e32 v150, 19, v151
	v_mul_f32_e32 v123, v123, v126
	v_mul_f32_e32 v123, v127, v123
	v_cvt_pk_bf16_f32 v126, v123, s0
	v_mad_i64_i32 v[122:123], s[42:43], v122, s56, v[136:137]
	global_store_short v[122:123], v126, off
	v_mul_f32_e32 v126, 0xbfb8aa3b, v112
	v_exp_f32_e32 v126, v126
	v_add_u32_e32 v149, 32, v151
	v_add_u32_e32 v148, 33, v151
	v_add_u32_e32 v147, 34, v151
	v_add_f32_e32 v126, 1.0, v126
	v_rcp_f32_e32 v126, v126
	v_add_u32_e32 v146, 35, v151
	v_add_u32_e32 v145, 48, v151
	v_add_u32_e32 v144, 49, v151
	v_mul_f32_e32 v112, v112, v126
	v_mul_f32_e32 v112, v116, v112
	v_cvt_pk_bf16_f32 v112, v112, s0
	global_store_short v[152:153], v112, off offset:32
	v_mul_f32_e32 v112, 0xbfb8aa3b, v113
	v_exp_f32_e32 v112, v112
	v_add_u32_e32 v143, 50, v151
	v_add_u32_e32 v142, 51, v151
	v_add_f32_e32 v112, 1.0, v112
	v_rcp_f32_e32 v112, v112
	s_nop 0
	v_mul_f32_e32 v112, v113, v112
	v_mul_f32_e32 v112, v117, v112
	v_cvt_pk_bf16_f32 v112, v112, s0
	global_store_short v[120:121], v112, off offset:32
	v_mul_f32_e32 v112, 0xbfb8aa3b, v114
	v_exp_f32_e32 v112, v112
	s_nop 0
	v_add_f32_e32 v112, 1.0, v112
	v_rcp_f32_e32 v112, v112
	s_nop 0
	v_mul_f32_e32 v112, v114, v112
	v_mul_f32_e32 v112, v118, v112
	v_cvt_pk_bf16_f32 v112, v112, s0
	global_store_short v[124:125], v112, off offset:32
	v_mul_f32_e32 v112, 0xbfb8aa3b, v115
	v_exp_f32_e32 v112, v112
	s_nop 0
	v_add_f32_e32 v112, 1.0, v112
	v_rcp_f32_e32 v112, v112
	s_nop 0
	v_mul_f32_e32 v112, v115, v112
	v_mul_f32_e32 v112, v119, v112
	v_cvt_pk_bf16_f32 v112, v112, s0
	global_store_short v[122:123], v112, off offset:32
	v_mul_f32_e32 v112, 0xbfb8aa3b, v104
	v_exp_f32_e32 v112, v112
	s_nop 0
	v_add_f32_e32 v112, 1.0, v112
	v_rcp_f32_e32 v112, v112
	s_nop 0
	v_mul_f32_e32 v104, v104, v112
	v_mul_f32_e32 v104, v108, v104
	v_cvt_pk_bf16_f32 v104, v104, s0
	v_mad_i64_i32 v[112:113], s[42:43], v154, s56, v[136:137]
	global_store_short v[112:113], v104, off
	v_mul_f32_e32 v104, 0xbfb8aa3b, v105
	v_exp_f32_e32 v104, v104
	s_nop 0
	v_add_f32_e32 v104, 1.0, v104
	v_rcp_f32_e32 v104, v104
	s_nop 0
	v_mul_f32_e32 v104, v105, v104
	v_mul_f32_e32 v104, v109, v104
	v_cvt_pk_bf16_f32 v108, v104, s0
	v_mad_i64_i32 v[104:105], s[42:43], v155, s56, v[136:137]
	global_store_short v[104:105], v108, off
	v_mul_f32_e32 v108, 0xbfb8aa3b, v106
	v_exp_f32_e32 v108, v108
	s_nop 0
	v_add_f32_e32 v108, 1.0, v108
	v_rcp_f32_e32 v108, v108
	s_nop 0
	v_mul_f32_e32 v106, v106, v108
	v_mul_f32_e32 v106, v110, v106
	v_cvt_pk_bf16_f32 v106, v106, s0
	v_mad_i64_i32 v[108:109], s[42:43], v156, s56, v[136:137]
	global_store_short v[108:109], v106, off
	v_mul_f32_e32 v106, 0xbfb8aa3b, v107
	v_exp_f32_e32 v106, v106
	s_nop 0
	v_add_f32_e32 v106, 1.0, v106
	v_rcp_f32_e32 v106, v106
	s_nop 0
	v_mul_f32_e32 v106, v107, v106
	v_mul_f32_e32 v106, v111, v106
	v_cvt_pk_bf16_f32 v110, v106, s0
	v_mad_i64_i32 v[106:107], s[42:43], v150, s56, v[136:137]
	global_store_short v[106:107], v110, off
	v_mul_f32_e32 v110, 0xbfb8aa3b, v96
	v_exp_f32_e32 v110, v110
	s_nop 0
	v_add_f32_e32 v110, 1.0, v110
	v_rcp_f32_e32 v110, v110
	s_nop 0
	v_mul_f32_e32 v96, v96, v110
	v_mul_f32_e32 v96, v100, v96
	v_cvt_pk_bf16_f32 v96, v96, s0
	global_store_short v[112:113], v96, off offset:32
	v_mul_f32_e32 v96, 0xbfb8aa3b, v97
	v_exp_f32_e32 v96, v96
	s_nop 0
	v_add_f32_e32 v96, 1.0, v96
	v_rcp_f32_e32 v96, v96
	s_nop 0
	v_mul_f32_e32 v96, v97, v96
	v_mul_f32_e32 v96, v101, v96
	v_cvt_pk_bf16_f32 v96, v96, s0
	global_store_short v[104:105], v96, off offset:32
	v_mul_f32_e32 v96, 0xbfb8aa3b, v98
	v_exp_f32_e32 v96, v96
	s_nop 0
	v_add_f32_e32 v96, 1.0, v96
	v_rcp_f32_e32 v96, v96
	s_nop 0
	v_mul_f32_e32 v96, v98, v96
	v_mul_f32_e32 v96, v102, v96
	v_cvt_pk_bf16_f32 v96, v96, s0
	global_store_short v[108:109], v96, off offset:32
	v_mul_f32_e32 v96, 0xbfb8aa3b, v99
	v_exp_f32_e32 v96, v96
	s_nop 0
	v_add_f32_e32 v96, 1.0, v96
	v_rcp_f32_e32 v96, v96
	s_nop 0
	v_mul_f32_e32 v96, v99, v96
	v_mul_f32_e32 v96, v103, v96
	v_cvt_pk_bf16_f32 v96, v96, s0
	global_store_short v[106:107], v96, off offset:32
	v_mul_f32_e32 v96, 0xbfb8aa3b, v88
	v_exp_f32_e32 v96, v96
	s_nop 0
	v_add_f32_e32 v96, 1.0, v96
	v_rcp_f32_e32 v96, v96
	s_nop 0
	v_mul_f32_e32 v88, v88, v96
; __device__ __forceinline__ float silu_f(float x) { return x * __builtin_amdgcn_rcpf(1.f + __expf(-x)); }
;   __device__ __forceinline__ void operator()(int brow, int bcol, int wr, int wc, int fr, int fq, f32x4 (&acc)[4][4], int split) const {
;     ...
; #pragma unroll
;     for (int m = 0; m < 4; m++)
; #pragma unroll
;       for (int pr = 0; pr < 2; pr++)
; #pragma unroll
;         for (int j = 0; j < 4; j++) {
;           int row = brow + wr * 64 + m * 16 + fq * 4 + j;
;           int col = (bcol >> 1) + wc * 32 + pr * 16 + fr;
;           float g = acc[m][2 * pr][j], u = acc[m][2 * pr + 1][j];
;           act[(size_t)row * DFF + col] = f2bf(silu_f(g) * u);
;         }
	v_mul_f32_e32 v88, v92, v88
	v_cvt_pk_bf16_f32 v88, v88, s0
	v_mad_i64_i32 v[96:97], s[42:43], v149, s56, v[136:137]
	global_store_short v[96:97], v88, off
	v_mul_f32_e32 v88, 0xbfb8aa3b, v89
	v_exp_f32_e32 v88, v88
	s_nop 0
	v_add_f32_e32 v88, 1.0, v88
	v_rcp_f32_e32 v88, v88
	s_nop 0
	v_mul_f32_e32 v88, v89, v88
	v_mul_f32_e32 v88, v93, v88
	v_cvt_pk_bf16_f32 v92, v88, s0
	v_mad_i64_i32 v[88:89], s[42:43], v148, s56, v[136:137]
	global_store_short v[88:89], v92, off
	v_mul_f32_e32 v92, 0xbfb8aa3b, v90
	v_exp_f32_e32 v92, v92
	s_nop 0
	v_add_f32_e32 v92, 1.0, v92
	v_rcp_f32_e32 v92, v92
	s_nop 0
	v_mul_f32_e32 v90, v90, v92
	v_mul_f32_e32 v90, v94, v90
	v_cvt_pk_bf16_f32 v90, v90, s0
	v_mad_i64_i32 v[92:93], s[42:43], v147, s56, v[136:137]
	global_store_short v[92:93], v90, off
	v_mul_f32_e32 v90, 0xbfb8aa3b, v91
	v_exp_f32_e32 v90, v90
	s_nop 0
	v_add_f32_e32 v90, 1.0, v90
	v_rcp_f32_e32 v90, v90
	s_nop 0
	v_mul_f32_e32 v90, v91, v90
	v_mul_f32_e32 v90, v95, v90
	v_cvt_pk_bf16_f32 v94, v90, s0
	v_mad_i64_i32 v[90:91], s[42:43], v146, s56, v[136:137]
	global_store_short v[90:91], v94, off
	v_mul_f32_e32 v94, 0xbfb8aa3b, v80
	v_exp_f32_e32 v94, v94
	s_nop 0
	v_add_f32_e32 v94, 1.0, v94
	v_rcp_f32_e32 v94, v94
	s_nop 0
	v_mul_f32_e32 v80, v80, v94
	v_mul_f32_e32 v80, v84, v80
	v_cvt_pk_bf16_f32 v80, v80, s0
	global_store_short v[96:97], v80, off offset:32
	v_mul_f32_e32 v80, 0xbfb8aa3b, v81
	v_exp_f32_e32 v80, v80
	s_nop 0
	v_add_f32_e32 v80, 1.0, v80
	v_rcp_f32_e32 v80, v80
	s_nop 0
	v_mul_f32_e32 v80, v81, v80
	v_mul_f32_e32 v80, v85, v80
	v_cvt_pk_bf16_f32 v80, v80, s0
	global_store_short v[88:89], v80, off offset:32
	v_mul_f32_e32 v80, 0xbfb8aa3b, v82
	v_exp_f32_e32 v80, v80
	s_nop 0
	v_add_f32_e32 v80, 1.0, v80
	v_rcp_f32_e32 v80, v80
	s_nop 0
	v_mul_f32_e32 v80, v82, v80
	v_mul_f32_e32 v80, v86, v80
	v_cvt_pk_bf16_f32 v80, v80, s0
	global_store_short v[92:93], v80, off offset:32
	v_mul_f32_e32 v80, 0xbfb8aa3b, v83
	v_exp_f32_e32 v80, v80
	s_nop 0
	v_add_f32_e32 v80, 1.0, v80
	v_rcp_f32_e32 v80, v80
	s_nop 0
	v_mul_f32_e32 v80, v83, v80
	v_mul_f32_e32 v80, v87, v80
	v_cvt_pk_bf16_f32 v80, v80, s0
	global_store_short v[90:91], v80, off offset:32
	v_mul_f32_e32 v80, 0xbfb8aa3b, v72
	v_exp_f32_e32 v80, v80
	s_nop 0
	v_add_f32_e32 v80, 1.0, v80
	v_rcp_f32_e32 v80, v80
	s_nop 0
	v_mul_f32_e32 v72, v72, v80
	v_mul_f32_e32 v72, v76, v72
	v_cvt_pk_bf16_f32 v72, v72, s0
	v_mad_i64_i32 v[80:81], s[42:43], v145, s56, v[136:137]
	global_store_short v[80:81], v72, off
	v_mul_f32_e32 v72, 0xbfb8aa3b, v73
	v_exp_f32_e32 v72, v72
	s_nop 0
	v_add_f32_e32 v72, 1.0, v72
	v_rcp_f32_e32 v72, v72
	s_nop 0
	v_mul_f32_e32 v72, v73, v72
	v_mul_f32_e32 v72, v77, v72
	v_cvt_pk_bf16_f32 v76, v72, s0
	v_mad_i64_i32 v[72:73], s[42:43], v144, s56, v[136:137]
	global_store_short v[72:73], v76, off
	v_mul_f32_e32 v76, 0xbfb8aa3b, v74
	v_exp_f32_e32 v76, v76
	s_nop 0
	v_add_f32_e32 v76, 1.0, v76
	v_rcp_f32_e32 v76, v76
	s_nop 0
	v_mul_f32_e32 v74, v74, v76
	v_mul_f32_e32 v74, v78, v74
	v_cvt_pk_bf16_f32 v74, v74, s0
	v_mad_i64_i32 v[76:77], s[42:43], v143, s56, v[136:137]
	global_store_short v[76:77], v74, off
	v_mul_f32_e32 v74, 0xbfb8aa3b, v75
	v_exp_f32_e32 v74, v74
	s_nop 0
	v_add_f32_e32 v74, 1.0, v74
	v_rcp_f32_e32 v74, v74
	s_nop 0
	v_mul_f32_e32 v74, v75, v74
	v_mul_f32_e32 v74, v79, v74
	v_cvt_pk_bf16_f32 v78, v74, s0
	v_mad_i64_i32 v[74:75], s[42:43], v142, s56, v[136:137]
	global_store_short v[74:75], v78, off
	v_mul_f32_e32 v78, 0xbfb8aa3b, v64
	v_exp_f32_e32 v78, v78
	s_nop 0
	v_add_f32_e32 v78, 1.0, v78
	v_rcp_f32_e32 v78, v78
	s_nop 0
	v_mul_f32_e32 v64, v64, v78
	v_mul_f32_e32 v64, v68, v64
	v_cvt_pk_bf16_f32 v64, v64, s0
	global_store_short v[80:81], v64, off offset:32
	v_mul_f32_e32 v64, 0xbfb8aa3b, v65
	v_exp_f32_e32 v64, v64
	s_nop 0
	v_add_f32_e32 v64, 1.0, v64
	v_rcp_f32_e32 v64, v64
	s_nop 0
	v_mul_f32_e32 v64, v65, v64
	v_mul_f32_e32 v64, v69, v64
	v_cvt_pk_bf16_f32 v64, v64, s0
	global_store_short v[72:73], v64, off offset:32
	v_mul_f32_e32 v64, 0xbfb8aa3b, v66
	v_exp_f32_e32 v64, v64
	s_nop 0
	v_add_f32_e32 v64, 1.0, v64
	v_rcp_f32_e32 v64, v64
	s_nop 0
	v_mul_f32_e32 v64, v66, v64
	v_mul_f32_e32 v64, v70, v64
	v_cvt_pk_bf16_f32 v64, v64, s0
	global_store_short v[76:77], v64, off offset:32
	v_mul_f32_e32 v64, 0xbfb8aa3b, v67
	v_exp_f32_e32 v64, v64
	s_nop 0
	v_add_f32_e32 v64, 1.0, v64
	v_rcp_f32_e32 v64, v64
	s_nop 0
	v_mul_f32_e32 v64, v67, v64
	v_mul_f32_e32 v64, v71, v64
	v_cvt_pk_bf16_f32 v64, v64, s0
	global_store_short v[74:75], v64, off offset:32
	v_mul_f32_e32 v74, 0xbfb8aa3b, v56
	v_exp_f32_e32 v74, v74
	v_add_u32_e32 v73, s46, v141
	v_add_u32_e32 v76, 16, v73
	v_add_u32_e32 v77, 17, v73
	v_add_f32_e32 v74, 1.0, v74
	v_rcp_f32_e32 v74, v74
	v_add_u32_e32 v78, 18, v73
	v_add_u32_e32 v72, 19, v73
	v_add_u32_e32 v71, 32, v73
	v_mul_f32_e32 v56, v56, v74
	v_mul_f32_e32 v56, v60, v56
	v_mul_f32_e32 v60, 0xbfb8aa3b, v57
	v_exp_f32_e32 v60, v60
	v_cvt_pk_bf16_f32 v56, v56, s0
	v_mad_i64_i32 v[74:75], s[42:43], v73, s56, v[136:137]
	v_add_f32_e32 v60, 1.0, v60
	v_rcp_f32_e32 v60, v60
	global_store_short v[74:75], v56, off
	v_add_u32_e32 v56, 1, v73
	v_add_u32_e32 v70, 33, v73
	v_mul_f32_e32 v57, v57, v60
	v_mul_f32_e32 v57, v61, v57
	v_mul_f32_e32 v61, 0xbfb8aa3b, v58
	v_exp_f32_e32 v61, v61
	v_cvt_pk_bf16_f32 v60, v57, s0
	v_mad_i64_i32 v[56:57], s[42:43], v56, s56, v[136:137]
	v_add_f32_e32 v61, 1.0, v61
	v_rcp_f32_e32 v61, v61
	global_store_short v[56:57], v60, off
	v_add_u32_e32 v60, 2, v73
	v_add_u32_e32 v69, 34, v73
	v_mul_f32_e32 v58, v58, v61
	v_mul_f32_e32 v58, v62, v58
	v_mul_f32_e32 v62, 0xbfb8aa3b, v59
	v_exp_f32_e32 v62, v62
; __device__ __forceinline__ float silu_f(float x) { return x * __builtin_amdgcn_rcpf(1.f + __expf(-x)); }
;   __device__ __forceinline__ void operator()(int brow, int bcol, int wr, int wc, int fr, int fq, f32x4 (&acc)[4][4], int split) const {
;     ...
; #pragma unroll
;     for (int m = 0; m < 4; m++)
; #pragma unroll
;       for (int pr = 0; pr < 2; pr++)
; #pragma unroll
;         for (int j = 0; j < 4; j++) {
;           int row = brow + wr * 64 + m * 16 + fq * 4 + j;
;           int col = (bcol >> 1) + wc * 32 + pr * 16 + fr;
;           float g = acc[m][2 * pr][j], u = acc[m][2 * pr + 1][j];
;           act[(size_t)row * DFF + col] = f2bf(silu_f(g) * u);
;         }
	v_cvt_pk_bf16_f32 v58, v58, s0
	v_mad_i64_i32 v[60:61], s[42:43], v60, s56, v[136:137]
	v_add_f32_e32 v62, 1.0, v62
	v_rcp_f32_e32 v62, v62
	global_store_short v[60:61], v58, off
	v_add_u32_e32 v58, 3, v73
	v_add_u32_e32 v68, 35, v73
	v_mul_f32_e32 v59, v59, v62
	v_mul_f32_e32 v59, v63, v59
	v_cvt_pk_bf16_f32 v62, v59, s0
	v_mad_i64_i32 v[58:59], s[42:43], v58, s56, v[136:137]
	global_store_short v[58:59], v62, off
	v_mul_f32_e32 v62, 0xbfb8aa3b, v48
	v_exp_f32_e32 v62, v62
	v_add_u32_e32 v67, 48, v73
	v_add_u32_e32 v66, 49, v73
	v_add_u32_e32 v65, 50, v73
	v_add_f32_e32 v62, 1.0, v62
	v_rcp_f32_e32 v62, v62
	v_add_u32_e32 v64, 51, v73
	v_mul_f32_e32 v48, v48, v62
	v_mul_f32_e32 v48, v52, v48
	v_cvt_pk_bf16_f32 v48, v48, s0
	global_store_short v[74:75], v48, off offset:32
	v_mul_f32_e32 v48, 0xbfb8aa3b, v49
	v_exp_f32_e32 v48, v48
	s_nop 0
	v_add_f32_e32 v48, 1.0, v48
	v_rcp_f32_e32 v48, v48
	s_nop 0
	v_mul_f32_e32 v48, v49, v48
	v_mul_f32_e32 v48, v53, v48
	v_cvt_pk_bf16_f32 v48, v48, s0
	global_store_short v[56:57], v48, off offset:32
	v_mul_f32_e32 v48, 0xbfb8aa3b, v50
	v_exp_f32_e32 v48, v48
	s_nop 0
	v_add_f32_e32 v48, 1.0, v48
	v_rcp_f32_e32 v48, v48
	s_nop 0
	v_mul_f32_e32 v48, v50, v48
	v_mul_f32_e32 v48, v54, v48
	v_cvt_pk_bf16_f32 v48, v48, s0
	global_store_short v[60:61], v48, off offset:32
	v_mul_f32_e32 v48, 0xbfb8aa3b, v51
	v_exp_f32_e32 v48, v48
	s_nop 0
	v_add_f32_e32 v48, 1.0, v48
	v_rcp_f32_e32 v48, v48
	s_nop 0
	v_mul_f32_e32 v48, v51, v48
	v_mul_f32_e32 v48, v55, v48
	v_cvt_pk_bf16_f32 v48, v48, s0
	global_store_short v[58:59], v48, off offset:32
	v_mul_f32_e32 v48, 0xbfb8aa3b, v40
	v_exp_f32_e32 v48, v48
	s_nop 0
	v_add_f32_e32 v48, 1.0, v48
	v_rcp_f32_e32 v48, v48
	s_nop 0
	v_mul_f32_e32 v40, v40, v48
	v_mul_f32_e32 v40, v44, v40
	v_cvt_pk_bf16_f32 v40, v40, s0
	v_mad_i64_i32 v[48:49], s[42:43], v76, s56, v[136:137]
	global_store_short v[48:49], v40, off
	v_mul_f32_e32 v40, 0xbfb8aa3b, v41
	v_exp_f32_e32 v40, v40
	s_nop 0
	v_add_f32_e32 v40, 1.0, v40
	v_rcp_f32_e32 v40, v40
	s_nop 0
	v_mul_f32_e32 v40, v41, v40
	v_mul_f32_e32 v40, v45, v40
	v_cvt_pk_bf16_f32 v44, v40, s0
	v_mad_i64_i32 v[40:41], s[42:43], v77, s56, v[136:137]
	global_store_short v[40:41], v44, off
	v_mul_f32_e32 v44, 0xbfb8aa3b, v42
	v_exp_f32_e32 v44, v44
	s_nop 0
	v_add_f32_e32 v44, 1.0, v44
	v_rcp_f32_e32 v44, v44
	s_nop 0
	v_mul_f32_e32 v42, v42, v44
	v_mul_f32_e32 v42, v46, v42
	v_cvt_pk_bf16_f32 v42, v42, s0
	v_mad_i64_i32 v[44:45], s[42:43], v78, s56, v[136:137]
	global_store_short v[44:45], v42, off
	v_mul_f32_e32 v42, 0xbfb8aa3b, v43
	v_exp_f32_e32 v42, v42
	s_nop 0
	v_add_f32_e32 v42, 1.0, v42
	v_rcp_f32_e32 v42, v42
	s_nop 0
	v_mul_f32_e32 v42, v43, v42
	v_mul_f32_e32 v42, v47, v42
	v_cvt_pk_bf16_f32 v46, v42, s0
	v_mad_i64_i32 v[42:43], s[42:43], v72, s56, v[136:137]
	global_store_short v[42:43], v46, off
	v_mul_f32_e32 v46, 0xbfb8aa3b, v32
	v_exp_f32_e32 v46, v46
	s_nop 0
	v_add_f32_e32 v46, 1.0, v46
	v_rcp_f32_e32 v46, v46
	s_nop 0
	v_mul_f32_e32 v32, v32, v46
	v_mul_f32_e32 v32, v36, v32
	v_cvt_pk_bf16_f32 v32, v32, s0
	global_store_short v[48:49], v32, off offset:32
	v_mul_f32_e32 v32, 0xbfb8aa3b, v33
	v_exp_f32_e32 v32, v32
	s_nop 0
	v_add_f32_e32 v32, 1.0, v32
	v_rcp_f32_e32 v32, v32
	s_nop 0
	v_mul_f32_e32 v32, v33, v32
	v_mul_f32_e32 v32, v37, v32
	v_cvt_pk_bf16_f32 v32, v32, s0
	global_store_short v[40:41], v32, off offset:32
	v_mul_f32_e32 v32, 0xbfb8aa3b, v34
	v_exp_f32_e32 v32, v32
	s_nop 0
	v_add_f32_e32 v32, 1.0, v32
	v_rcp_f32_e32 v32, v32
	s_nop 0
	v_mul_f32_e32 v32, v34, v32
	v_mul_f32_e32 v32, v38, v32
	v_cvt_pk_bf16_f32 v32, v32, s0
	global_store_short v[44:45], v32, off offset:32
	v_mul_f32_e32 v32, 0xbfb8aa3b, v35
	v_exp_f32_e32 v32, v32
	s_nop 0
	v_add_f32_e32 v32, 1.0, v32
	v_rcp_f32_e32 v32, v32
	s_nop 0
	v_mul_f32_e32 v32, v35, v32
	v_mul_f32_e32 v32, v39, v32
	v_cvt_pk_bf16_f32 v32, v32, s0
	global_store_short v[42:43], v32, off offset:32
	v_mul_f32_e32 v32, 0xbfb8aa3b, v24
	v_exp_f32_e32 v32, v32
	s_nop 0
	v_add_f32_e32 v32, 1.0, v32
	v_rcp_f32_e32 v32, v32
	s_nop 0
	v_mul_f32_e32 v24, v24, v32
	v_mul_f32_e32 v24, v28, v24
	v_cvt_pk_bf16_f32 v24, v24, s0
	v_mad_i64_i32 v[32:33], s[42:43], v71, s56, v[136:137]
	global_store_short v[32:33], v24, off
	v_mul_f32_e32 v24, 0xbfb8aa3b, v25
	v_exp_f32_e32 v24, v24
; __device__ __forceinline__ float silu_f(float x) { return x * __builtin_amdgcn_rcpf(1.f + __expf(-x)); }
; template <class Epi>
; __device__ __forceinline__ void gemm_phase(const bfr* __restrict__ A, int lda, const bfr* __restrict__ Bt, int K,
;                                            int nM, int nN, const Epi& epi, bfr* shm, int wv, int nMfull, int ksplit) {
;     ...
;     item = nitem; brow = nbrow; bcol = nbcol; kbeg = nkbeg; nt = nnt; split = nsplit;
;   __device__ __forceinline__ void operator()(int brow, int bcol, int wr, int wc, int fr, int fq, f32x4 (&acc)[4][4], int split) const {
;     ...
; #pragma unroll
;     for (int m = 0; m < 4; m++)
; #pragma unroll
;       for (int pr = 0; pr < 2; pr++)
; #pragma unroll
;         for (int j = 0; j < 4; j++) {
;           int row = brow + wr * 64 + m * 16 + fq * 4 + j;
;           int col = (bcol >> 1) + wc * 32 + pr * 16 + fr;
;           float g = acc[m][2 * pr][j], u = acc[m][2 * pr + 1][j];
;           act[(size_t)row * DFF + col] = f2bf(silu_f(g) * u);
;         }
	s_nop 0
	v_add_f32_e32 v24, 1.0, v24
	v_rcp_f32_e32 v24, v24
	s_nop 0
	v_mul_f32_e32 v24, v25, v24
	v_mul_f32_e32 v24, v29, v24
	v_cvt_pk_bf16_f32 v28, v24, s0
	v_mad_i64_i32 v[24:25], s[42:43], v70, s56, v[136:137]
	global_store_short v[24:25], v28, off
	v_mul_f32_e32 v28, 0xbfb8aa3b, v26
	v_exp_f32_e32 v28, v28
	s_nop 0
	v_add_f32_e32 v28, 1.0, v28
	v_rcp_f32_e32 v28, v28
	s_nop 0
	v_mul_f32_e32 v26, v26, v28
	v_mul_f32_e32 v26, v30, v26
	v_cvt_pk_bf16_f32 v26, v26, s0
	v_mad_i64_i32 v[28:29], s[42:43], v69, s56, v[136:137]
	global_store_short v[28:29], v26, off
	v_mul_f32_e32 v26, 0xbfb8aa3b, v27
	v_exp_f32_e32 v26, v26
	s_nop 0
	v_add_f32_e32 v26, 1.0, v26
	v_rcp_f32_e32 v26, v26
	s_nop 0
	v_mul_f32_e32 v26, v27, v26
	v_mul_f32_e32 v26, v31, v26
	v_cvt_pk_bf16_f32 v30, v26, s0
	v_mad_i64_i32 v[26:27], s[42:43], v68, s56, v[136:137]
	global_store_short v[26:27], v30, off
	v_mul_f32_e32 v30, 0xbfb8aa3b, v16
	v_exp_f32_e32 v30, v30
	s_nop 0
	v_add_f32_e32 v30, 1.0, v30
	v_rcp_f32_e32 v30, v30
	s_nop 0
	v_mul_f32_e32 v16, v16, v30
	v_mul_f32_e32 v16, v20, v16
	v_cvt_pk_bf16_f32 v16, v16, s0
	global_store_short v[32:33], v16, off offset:32
	v_mul_f32_e32 v16, 0xbfb8aa3b, v17
	v_exp_f32_e32 v16, v16
	s_nop 0
	v_add_f32_e32 v16, 1.0, v16
	v_rcp_f32_e32 v16, v16
	s_nop 0
	v_mul_f32_e32 v16, v17, v16
	v_mul_f32_e32 v16, v21, v16
	v_cvt_pk_bf16_f32 v16, v16, s0
	global_store_short v[24:25], v16, off offset:32
	v_mul_f32_e32 v16, 0xbfb8aa3b, v18
	v_exp_f32_e32 v16, v16
	s_nop 0
	v_add_f32_e32 v16, 1.0, v16
	v_rcp_f32_e32 v16, v16
	s_nop 0
	v_mul_f32_e32 v16, v18, v16
	v_mul_f32_e32 v16, v22, v16
	v_cvt_pk_bf16_f32 v16, v16, s0
	global_store_short v[28:29], v16, off offset:32
	v_mul_f32_e32 v16, 0xbfb8aa3b, v19
	v_exp_f32_e32 v16, v16
	s_nop 0
	v_add_f32_e32 v16, 1.0, v16
	v_rcp_f32_e32 v16, v16
	s_nop 0
	v_mul_f32_e32 v16, v19, v16
	v_mul_f32_e32 v16, v23, v16
	v_cvt_pk_bf16_f32 v16, v16, s0
	global_store_short v[26:27], v16, off offset:32
	v_mul_f32_e32 v16, 0xbfb8aa3b, v8
	v_exp_f32_e32 v16, v16
	s_nop 0
	v_add_f32_e32 v16, 1.0, v16
	v_rcp_f32_e32 v16, v16
	s_nop 0
	v_mul_f32_e32 v8, v8, v16
	v_mul_f32_e32 v8, v12, v8
	v_cvt_pk_bf16_f32 v8, v8, s0
	v_mad_i64_i32 v[16:17], s[42:43], v67, s56, v[136:137]
	global_store_short v[16:17], v8, off
	v_mul_f32_e32 v8, 0xbfb8aa3b, v9
	v_exp_f32_e32 v8, v8
	s_nop 0
	v_add_f32_e32 v8, 1.0, v8
	v_rcp_f32_e32 v8, v8
	s_nop 0
	v_mul_f32_e32 v8, v9, v8
	v_mul_f32_e32 v8, v13, v8
	v_cvt_pk_bf16_f32 v12, v8, s0
	v_mad_i64_i32 v[8:9], s[42:43], v66, s56, v[136:137]
	global_store_short v[8:9], v12, off
	v_mul_f32_e32 v12, 0xbfb8aa3b, v10
	v_exp_f32_e32 v12, v12
	s_nop 0
	v_add_f32_e32 v12, 1.0, v12
	v_rcp_f32_e32 v12, v12
	s_nop 0
	v_mul_f32_e32 v10, v10, v12
	v_mul_f32_e32 v10, v14, v10
	v_cvt_pk_bf16_f32 v10, v10, s0
	v_mad_i64_i32 v[12:13], s[42:43], v65, s56, v[136:137]
	global_store_short v[12:13], v10, off
	v_mul_f32_e32 v10, 0xbfb8aa3b, v11
	v_exp_f32_e32 v10, v10
	s_nop 0
	v_add_f32_e32 v10, 1.0, v10
	v_rcp_f32_e32 v10, v10
	s_nop 0
	v_mul_f32_e32 v10, v11, v10
	v_mul_f32_e32 v10, v15, v10
	v_cvt_pk_bf16_f32 v14, v10, s0
	v_mad_i64_i32 v[10:11], s[42:43], v64, s56, v[136:137]
	global_store_short v[10:11], v14, off
	v_mul_f32_e32 v14, 0xbfb8aa3b, v0
	v_exp_f32_e32 v14, v14
	s_nop 0
	v_add_f32_e32 v14, 1.0, v14
	v_rcp_f32_e32 v14, v14
	s_nop 0
	v_mul_f32_e32 v0, v0, v14
	v_mul_f32_e32 v0, v4, v0
	v_cvt_pk_bf16_f32 v0, v0, s0
	global_store_short v[16:17], v0, off offset:32
	v_mul_f32_e32 v0, 0xbfb8aa3b, v1
	v_exp_f32_e32 v0, v0
	s_nop 0
	v_add_f32_e32 v0, 1.0, v0
	v_rcp_f32_e32 v0, v0
	s_nop 0
	v_mul_f32_e32 v0, v1, v0
	v_mul_f32_e32 v0, v5, v0
	v_cvt_pk_bf16_f32 v0, v0, s0
	global_store_short v[8:9], v0, off offset:32
	v_mul_f32_e32 v0, 0xbfb8aa3b, v2
	v_exp_f32_e32 v0, v0
	s_nop 0
	v_add_f32_e32 v0, 1.0, v0
	v_rcp_f32_e32 v0, v0
	s_nop 0
	v_mul_f32_e32 v0, v2, v0
	v_mul_f32_e32 v0, v6, v0
	v_cvt_pk_bf16_f32 v0, v0, s0
	global_store_short v[12:13], v0, off offset:32
	v_mul_f32_e32 v0, 0xbfb8aa3b, v3
	v_exp_f32_e32 v0, v0
	s_nop 0
	v_add_f32_e32 v0, 1.0, v0
	v_rcp_f32_e32 v0, v0
	s_nop 0
	v_mul_f32_e32 v0, v3, v0
	v_mul_f32_e32 v0, v7, v0
	v_cvt_pk_bf16_f32 v0, v0, s0
	global_store_short v[10:11], v0, off offset:32
	s_andn2_b64 vcc, exec, s[36:37]
	s_mov_b32 s42, s38
	s_mov_b32 s44, s40
	s_cbranch_vccz .LBB0_200

; #define STAGE(P, BASE, br, kt) do { const char* _g = (const char*)((BASE) + (size_t)(br) * K + (size_t)(kt) * G_BK); \
;     _Pragma("unroll") for (int _i = 0; _i < 2; ++_i) { \
;       __builtin_amdgcn_global_load_lds((const unsigned*)(_g + (size_t)_i * 128 * K + sg_off), (unsigned*)((char*)(P) + wid * 1024 + _i * 8192), 16, 0, 0); } } while (0)
; #define LDA(dst, b, h) _Pragma("unroll") for (int m = 0; m < 4; ++m) _Pragma("unroll") for (int k = 0; k < 2; ++k) \
;     dst[m][k] = *reinterpret_cast<const bf16x8*>((const char*)shm + aoff + (((b) * 2 + (h)) * 16384 + m * 2048 + k * 1024))
; #define LDB(dst, b, h) _Pragma("unroll") for (int n = 0; n < 2; ++n) _Pragma("unroll") for (int k = 0; k < 2; ++k) \
;     dst[n][k] = *reinterpret_cast<const bf16x8*>((const char*)shm + boff + (((b) * 2 + (h)) * 16384 + n * 2048 + k * 1024))
; #define MMA(ai, bj, At, Bt_) do { __builtin_amdgcn_s_setprio(1); \
;     _Pragma("unroll") for (int m = 0; m < 4; ++m) _Pragma("unroll") for (int n = 0; n < 2; ++n) _Pragma("unroll") for (int k = 0; k < 2; ++k) \
;       acc[ai][bj][m][n] = mfma16(At[m][k], Bt_[n][k], acc[ai][bj][m][n]); \
;     __builtin_amdgcn_s_setprio(0); } while (0)
; #define WAIT_V(n) asm volatile("s_waitcnt vmcnt(" #n ")" ::: "memory")
; #define WAIT_L(n) asm volatile("s_waitcnt lgkmcnt(" #n ")" ::: "memory")
; #define BAR __builtin_amdgcn_s_barrier()
; #define SCHED __builtin_amdgcn_sched_barrier(0)
; template <class Epi>
; __device__ __forceinline__ void gemm_phase(const bfr* __restrict__ A, int lda, const bfr* __restrict__ Bt, int K,
;                                            int nM, int nN, const Epi& epi, bfr* shm, int wv, int nMfull, int ksplit) {
;     ...
;     f32x4 acc[2][2][4][2];
; #pragma unroll
;     for (int a = 0; a < 2; a++)
; #pragma unroll
;       for (int b = 0; b < 2; b++)
; #pragma unroll
;         for (int m = 0; m < 4; m++)
; #pragma unroll
;           for (int n = 0; n < 2; n++) acc[a][b][m][n] = f32x4{0.f, 0.f, 0.f, 0.f};
;     bf16x8 At[4][2], B0[2][2], B1[2][2];
;     if (wr == 1) BAR;
;     WAIT_V(10); BAR;
;     WAIT_V(6); BAR;
;     for (int t = 0; t < nt - 2; t += 2) {
;       LDB(B0, 0, 0); SCHED; LDA(At, 0, 0); STAGE(SA(1, 1), Ak, brow + G_HALF, t + 1);
;       WAIT_L(8); BAR; WAIT_L(0); MMA(0, 0, At, B0); BAR; SCHED;
.LBB0_193:
	s_waitcnt vmcnt(10)
	s_barrier
	s_waitcnt vmcnt(6)
	v_mov_b32_e32 v127, 0
	s_cmp_lt_u32 s30, 3
	v_mov_b32_e32 v126, v127
	v_mov_b32_e32 v125, v127
	v_mov_b32_e32 v124, v127
	v_mov_b32_e32 v123, v127
	v_mov_b32_e32 v122, v127
	v_mov_b32_e32 v121, v127
	v_mov_b32_e32 v120, v127
	v_mov_b32_e32 v119, v127
	v_mov_b32_e32 v118, v127
	v_mov_b32_e32 v117, v127
	v_mov_b32_e32 v116, v127
	v_mov_b32_e32 v115, v127
	v_mov_b32_e32 v114, v127
	v_mov_b32_e32 v113, v127
	v_mov_b32_e32 v112, v127
	v_mov_b32_e32 v111, v127
	v_mov_b32_e32 v110, v127
	v_mov_b32_e32 v109, v127
	v_mov_b32_e32 v108, v127
	v_mov_b32_e32 v107, v127
	v_mov_b32_e32 v106, v127
	v_mov_b32_e32 v105, v127
	v_mov_b32_e32 v104, v127
	v_mov_b32_e32 v103, v127
	v_mov_b32_e32 v102, v127
	v_mov_b32_e32 v101, v127
	v_mov_b32_e32 v100, v127
	v_mov_b32_e32 v99, v127
	v_mov_b32_e32 v98, v127
	v_mov_b32_e32 v97, v127
	v_mov_b32_e32 v96, v127
	v_mov_b32_e32 v95, v127
	v_mov_b32_e32 v94, v127
	v_mov_b32_e32 v93, v127
	v_mov_b32_e32 v92, v127
	v_mov_b32_e32 v91, v127
	v_mov_b32_e32 v90, v127
	v_mov_b32_e32 v89, v127
	v_mov_b32_e32 v88, v127
	v_mov_b32_e32 v87, v127
	v_mov_b32_e32 v86, v127
	v_mov_b32_e32 v85, v127
	v_mov_b32_e32 v84, v127
	v_mov_b32_e32 v83, v127
	v_mov_b32_e32 v82, v127
	v_mov_b32_e32 v81, v127
	v_mov_b32_e32 v80, v127
	v_mov_b32_e32 v79, v127
	v_mov_b32_e32 v78, v127
	v_mov_b32_e32 v77, v127
	v_mov_b32_e32 v76, v127
	v_mov_b32_e32 v75, v127
	v_mov_b32_e32 v74, v127
	v_mov_b32_e32 v73, v127
	v_mov_b32_e32 v72, v127
	v_mov_b32_e32 v71, v127
	v_mov_b32_e32 v70, v127
	v_mov_b32_e32 v69, v127
	v_mov_b32_e32 v68, v127
	v_mov_b32_e32 v67, v127
	v_mov_b32_e32 v66, v127
	v_mov_b32_e32 v65, v127
	v_mov_b32_e32 v64, v127
	v_mov_b32_e32 v63, v127
	v_mov_b32_e32 v62, v127
	v_mov_b32_e32 v61, v127
	v_mov_b32_e32 v60, v127
	v_mov_b32_e32 v59, v127
	v_mov_b32_e32 v58, v127
	v_mov_b32_e32 v57, v127
	v_mov_b32_e32 v56, v127
	v_mov_b32_e32 v55, v127
	v_mov_b32_e32 v54, v127
	v_mov_b32_e32 v53, v127
	v_mov_b32_e32 v52, v127
	v_mov_b32_e32 v51, v127
	v_mov_b32_e32 v50, v127
	v_mov_b32_e32 v49, v127
	v_mov_b32_e32 v48, v127
	v_mov_b32_e32 v47, v127
	v_mov_b32_e32 v46, v127
	v_mov_b32_e32 v45, v127
	v_mov_b32_e32 v44, v127
	v_mov_b32_e32 v43, v127
	v_mov_b32_e32 v42, v127
	v_mov_b32_e32 v41, v127
	v_mov_b32_e32 v40, v127
	v_mov_b32_e32 v39, v127
	v_mov_b32_e32 v38, v127
	v_mov_b32_e32 v37, v127
	v_mov_b32_e32 v36, v127
	v_mov_b32_e32 v35, v127
	v_mov_b32_e32 v34, v127
	v_mov_b32_e32 v33, v127
	v_mov_b32_e32 v32, v127
	v_mov_b32_e32 v31, v127
	v_mov_b32_e32 v30, v127
	v_mov_b32_e32 v29, v127
	v_mov_b32_e32 v28, v127
	v_mov_b32_e32 v27, v127
	v_mov_b32_e32 v26, v127
	v_mov_b32_e32 v25, v127
	v_mov_b32_e32 v24, v127
	v_mov_b32_e32 v23, v127
	v_mov_b32_e32 v22, v127
	v_mov_b32_e32 v21, v127
	v_mov_b32_e32 v20, v127
	v_mov_b32_e32 v19, v127
	v_mov_b32_e32 v18, v127
	v_mov_b32_e32 v17, v127
	v_mov_b32_e32 v16, v127
	v_mov_b32_e32 v15, v127
	v_mov_b32_e32 v14, v127
	v_mov_b32_e32 v13, v127
	v_mov_b32_e32 v12, v127
	v_mov_b32_e32 v11, v127
	v_mov_b32_e32 v10, v127
	v_mov_b32_e32 v9, v127
	v_mov_b32_e32 v8, v127
	v_mov_b32_e32 v7, v127
	v_mov_b32_e32 v6, v127
	v_mov_b32_e32 v5, v127
	v_mov_b32_e32 v4, v127
	v_mov_b32_e32 v3, v127
	v_mov_b32_e32 v2, v127
	v_mov_b32_e32 v1, v127
	v_mov_b32_e32 v0, v127
	s_barrier
	s_cbranch_scc1 .LBB0_196
	s_ashr_i32 s43, s42, 31
	s_ashr_i32 s45, s44, 31
	v_readlane_b32 s60, v254, 54
	s_add_i32 s31, s30, -2
	s_lshl_b64 s[36:37], s[42:43], 11
	s_lshl_b64 s[38:39], s[44:45], 11
	v_readlane_b32 s62, v254, 56
	v_readlane_b32 s63, v254, 57
	s_add_u32 s36, s62, s36
	s_addc_u32 s37, s63, s37
	s_add_u32 s38, s80, s38
	v_mov_b32_e32 v0, 0
	s_addc_u32 s39, s81, s39
	s_mov_b32 s40, 0
	v_readlane_b32 s61, v254, 55
	v_readlane_b32 s64, v254, 58
	v_readlane_b32 s65, v254, 59
	v_readlane_b32 s66, v254, 60
	v_readlane_b32 s67, v254, 61
	v_readlane_b32 s68, v254, 62
	v_readlane_b32 s69, v254, 63
	v_readlane_b32 s70, v255, 0
	v_readlane_b32 s71, v255, 1
	v_readlane_b32 s72, v255, 2
	v_readlane_b32 s73, v255, 3
	v_readlane_b32 s74, v255, 4
	v_readlane_b32 s75, v255, 5
.LBB0_195:
	ds_read_b128 v[142:145], v139
	ds_read_b128 v[146:149], v139 offset:1024
	ds_read_b128 v[150:153], v139 offset:2048
	ds_read_b128 v[154:157], v139 offset:3072
	v_lshl_add_u64 v[136:137], s[38:39], 0, v[134:135]
	s_mov_b64 s[46:47], 0x40080
	s_mov_b32 m0, s54
	v_lshl_add_u64 v[190:191], v[136:137], 0, s[46:47]
	s_mov_b64 s[46:47], 0x60080
	ds_read_b128 v[158:161], v138
	ds_read_b128 v[162:165], v138 offset:1024
	ds_read_b128 v[166:169], v138 offset:2048
	ds_read_b128 v[170:173], v138 offset:3072
	ds_read_b128 v[174:177], v138 offset:4096
	ds_read_b128 v[178:181], v138 offset:5120
	ds_read_b128 v[182:185], v138 offset:6144
	ds_read_b128 v[186:189], v138 offset:7168
	global_load_lds_dwordx4 v[190:191], off
	v_lshl_add_u64 v[190:191], v[136:137], 0, s[46:47]
	s_mov_b32 m0, s55
	s_nop 0
	global_load_lds_dwordx4 v[190:191], off
	s_waitcnt lgkmcnt(8)
	s_barrier
	s_waitcnt lgkmcnt(0)
	s_setprio 1
	s_waitcnt lgkmcnt(0)
	v_mfma_f32_16x16x32_bf16 v[124:127], v[158:161], v[142:145], v[124:127]
	v_mfma_f32_16x16x32_bf16 v[120:123], v[158:161], v[150:153], v[120:123]
	v_mfma_f32_16x16x32_bf16 v[116:119], v[166:169], v[142:145], v[116:119]
	v_mfma_f32_16x16x32_bf16 v[112:115], v[166:169], v[150:153], v[112:115]
	v_mfma_f32_16x16x32_bf16 v[108:111], v[174:177], v[142:145], v[108:111]
	v_mfma_f32_16x16x32_bf16 v[104:107], v[174:177], v[150:153], v[104:107]
	v_mfma_f32_16x16x32_bf16 v[100:103], v[182:185], v[142:145], v[100:103]
	v_mfma_f32_16x16x32_bf16 v[96:99], v[182:185], v[150:153], v[96:99]
	v_mfma_f32_16x16x32_bf16 v[124:127], v[162:165], v[146:149], v[124:127]
	v_mfma_f32_16x16x32_bf16 v[120:123], v[162:165], v[154:157], v[120:123]
	v_mfma_f32_16x16x32_bf16 v[116:119], v[170:173], v[146:149], v[116:119]
	v_mfma_f32_16x16x32_bf16 v[112:115], v[170:173], v[154:157], v[112:115]
	v_mfma_f32_16x16x32_bf16 v[108:111], v[178:181], v[146:149], v[108:111]
	v_mfma_f32_16x16x32_bf16 v[104:107], v[178:181], v[154:157], v[104:107]
	v_mfma_f32_16x16x32_bf16 v[100:103], v[186:189], v[146:149], v[100:103]
	v_mfma_f32_16x16x32_bf16 v[96:99], v[186:189], v[154:157], v[96:99]
	s_setprio 0
	s_barrier
; #define STAGE(P, BASE, br, kt) do { const char* _g = (const char*)((BASE) + (size_t)(br) * K + (size_t)(kt) * G_BK); \
;     _Pragma("unroll") for (int _i = 0; _i < 2; ++_i) { \
;       __builtin_amdgcn_global_load_lds((const unsigned*)(_g + (size_t)_i * 128 * K + sg_off), (unsigned*)((char*)(P) + wid * 1024 + _i * 8192), 16, 0, 0); } } while (0)
; #define LDA(dst, b, h) _Pragma("unroll") for (int m = 0; m < 4; ++m) _Pragma("unroll") for (int k = 0; k < 2; ++k) \
;     dst[m][k] = *reinterpret_cast<const bf16x8*>((const char*)shm + aoff + (((b) * 2 + (h)) * 16384 + m * 2048 + k * 1024))
; #define LDB(dst, b, h) _Pragma("unroll") for (int n = 0; n < 2; ++n) _Pragma("unroll") for (int k = 0; k < 2; ++k) \
;     dst[n][k] = *reinterpret_cast<const bf16x8*>((const char*)shm + boff + (((b) * 2 + (h)) * 16384 + n * 2048 + k * 1024))
; #define MMA(ai, bj, At, Bt_) do { __builtin_amdgcn_s_setprio(1); \
;     _Pragma("unroll") for (int m = 0; m < 4; ++m) _Pragma("unroll") for (int n = 0; n < 2; ++n) _Pragma("unroll") for (int k = 0; k < 2; ++k) \
;       acc[ai][bj][m][n] = mfma16(At[m][k], Bt_[n][k], acc[ai][bj][m][n]); \
;     __builtin_amdgcn_s_setprio(0); } while (0)
; #define WAIT_V(n) asm volatile("s_waitcnt vmcnt(" #n ")" ::: "memory")
; #define WAIT_L(n) asm volatile("s_waitcnt lgkmcnt(" #n ")" ::: "memory")
; #define BAR __builtin_amdgcn_s_barrier()
; #define SCHED __builtin_amdgcn_sched_barrier(0)
; template <class Epi>
; __device__ __forceinline__ void gemm_phase(const bfr* __restrict__ A, int lda, const bfr* __restrict__ Bt, int K,
;                                            int nM, int nN, const Epi& epi, bfr* shm, int wv, int nMfull, int ksplit) {
;     ...
;       LDB(B1, 0, 1); STAGE(SB(0, 0), Bk, bcol, t + 2);
;       BAR; WAIT_L(0); MMA(0, 1, At, B1); BAR;
;       LDA(At, 0, 1); STAGE(SA(0, 0), Ak, brow, t + 2);
;       BAR; WAIT_L(0); MMA(1, 0, At, B0); BAR; SCHED;
;       STAGE(SB(0, 1), Bk, bcol + G_HALF, t + 2);
;       WAIT_V(6); BAR; MMA(1, 1, At, B1); BAR;
;       LDB(B0, 1, 0); SCHED; LDA(At, 1, 0); STAGE(SA(0, 1), Ak, brow + G_HALF, t + 2);
;       WAIT_L(8); BAR; WAIT_L(0); MMA(0, 0, At, B0); BAR; SCHED;
	v_lshl_add_u64 v[206:207], s[36:37], 0, v[134:135]
	s_mov_b32 m0, s24
	v_lshl_add_u64 v[208:209], v[206:207], 0, s[10:11]
	ds_read_b128 v[190:193], v139 offset:16384
	ds_read_b128 v[194:197], v139 offset:17408
	ds_read_b128 v[198:201], v139 offset:18432
	ds_read_b128 v[202:205], v139 offset:19456
	global_load_lds_dwordx4 v[208:209], off
	v_lshl_add_u64 v[208:209], v[206:207], 0, s[12:13]
	s_mov_b32 m0, s25
	s_add_i32 s40, s40, 2
	global_load_lds_dwordx4 v[208:209], off
	s_barrier
	s_waitcnt lgkmcnt(0)
	s_setprio 1
	s_waitcnt lgkmcnt(0)
	v_mfma_f32_16x16x32_bf16 v[92:95], v[158:161], v[190:193], v[92:95]
	v_mfma_f32_16x16x32_bf16 v[88:91], v[158:161], v[198:201], v[88:91]
	v_mfma_f32_16x16x32_bf16 v[84:87], v[166:169], v[190:193], v[84:87]
	v_mfma_f32_16x16x32_bf16 v[80:83], v[166:169], v[198:201], v[80:83]
	v_mfma_f32_16x16x32_bf16 v[76:79], v[174:177], v[190:193], v[76:79]
	v_mfma_f32_16x16x32_bf16 v[72:75], v[174:177], v[198:201], v[72:75]
	v_mfma_f32_16x16x32_bf16 v[68:71], v[182:185], v[190:193], v[68:71]
	v_mfma_f32_16x16x32_bf16 v[64:67], v[182:185], v[198:201], v[64:67]
	v_mfma_f32_16x16x32_bf16 v[92:95], v[162:165], v[194:197], v[92:95]
	v_mfma_f32_16x16x32_bf16 v[88:91], v[162:165], v[202:205], v[88:91]
	v_mfma_f32_16x16x32_bf16 v[84:87], v[170:173], v[194:197], v[84:87]
	v_mfma_f32_16x16x32_bf16 v[80:83], v[170:173], v[202:205], v[80:83]
	v_mfma_f32_16x16x32_bf16 v[76:79], v[178:181], v[194:197], v[76:79]
	v_mfma_f32_16x16x32_bf16 v[72:75], v[178:181], v[202:205], v[72:75]
	v_mfma_f32_16x16x32_bf16 v[68:71], v[186:189], v[194:197], v[68:71]
	v_mfma_f32_16x16x32_bf16 v[64:67], v[186:189], v[202:205], v[64:67]
	s_setprio 0
	s_mov_b32 m0, s23
	v_lshl_add_u64 v[208:209], v[136:137], 0, s[10:11]
	s_barrier
	ds_read_b128 v[158:161], v138 offset:16384
	ds_read_b128 v[162:165], v138 offset:17408
	ds_read_b128 v[166:169], v138 offset:18432
	ds_read_b128 v[170:173], v138 offset:19456
	ds_read_b128 v[174:177], v138 offset:20480
	ds_read_b128 v[178:181], v138 offset:21504
	ds_read_b128 v[182:185], v138 offset:22528
	ds_read_b128 v[186:189], v138 offset:23552
	global_load_lds_dwordx4 v[208:209], off
	v_lshl_add_u64 v[208:209], v[136:137], 0, s[12:13]
	s_mov_b32 m0, s26
	s_nop 0
	global_load_lds_dwordx4 v[208:209], off
	s_barrier
	s_waitcnt lgkmcnt(0)
	s_setprio 1
	s_waitcnt lgkmcnt(0)
	v_mfma_f32_16x16x32_bf16 v[60:63], v[158:161], v[142:145], v[60:63]
	v_mfma_f32_16x16x32_bf16 v[56:59], v[158:161], v[150:153], v[56:59]
	v_mfma_f32_16x16x32_bf16 v[52:55], v[166:169], v[142:145], v[52:55]
	v_mfma_f32_16x16x32_bf16 v[48:51], v[166:169], v[150:153], v[48:51]
	v_mfma_f32_16x16x32_bf16 v[44:47], v[174:177], v[142:145], v[44:47]
	v_mfma_f32_16x16x32_bf16 v[40:43], v[174:177], v[150:153], v[40:43]
	v_mfma_f32_16x16x32_bf16 v[36:39], v[182:185], v[142:145], v[36:39]
	v_mfma_f32_16x16x32_bf16 v[32:35], v[182:185], v[150:153], v[32:35]
	v_mfma_f32_16x16x32_bf16 v[60:63], v[162:165], v[146:149], v[60:63]
	v_mfma_f32_16x16x32_bf16 v[56:59], v[162:165], v[154:157], v[56:59]
	v_mfma_f32_16x16x32_bf16 v[52:55], v[170:173], v[146:149], v[52:55]
	v_mfma_f32_16x16x32_bf16 v[48:51], v[170:173], v[154:157], v[48:51]
	v_mfma_f32_16x16x32_bf16 v[44:47], v[178:181], v[146:149], v[44:47]
	v_mfma_f32_16x16x32_bf16 v[40:43], v[178:181], v[154:157], v[40:43]
	v_mfma_f32_16x16x32_bf16 v[36:39], v[186:189], v[146:149], v[36:39]
	v_mfma_f32_16x16x32_bf16 v[32:35], v[186:189], v[154:157], v[32:35]
	s_setprio 0
	s_barrier
	s_mov_b32 m0, s27
	v_lshl_add_u64 v[142:143], v[206:207], 0, s[14:15]
	global_load_lds_dwordx4 v[142:143], off
	v_lshl_add_u64 v[142:143], v[206:207], 0, s[16:17]
	s_mov_b32 m0, s28
	s_nop 0
	global_load_lds_dwordx4 v[142:143], off
	s_waitcnt vmcnt(6)
	s_barrier
	s_setprio 1
	v_mfma_f32_16x16x32_bf16 v[28:31], v[158:161], v[190:193], v[28:31]
	v_mfma_f32_16x16x32_bf16 v[24:27], v[158:161], v[198:201], v[24:27]
	v_mfma_f32_16x16x32_bf16 v[20:23], v[166:169], v[190:193], v[20:23]
	v_mfma_f32_16x16x32_bf16 v[16:19], v[166:169], v[198:201], v[16:19]
	v_mfma_f32_16x16x32_bf16 v[12:15], v[174:177], v[190:193], v[12:15]
	v_mfma_f32_16x16x32_bf16 v[8:11], v[174:177], v[198:201], v[8:11]
	v_mfma_f32_16x16x32_bf16 v[4:7], v[182:185], v[190:193], v[4:7]
	v_mfma_f32_16x16x32_bf16 v[0:3], v[182:185], v[198:201], v[0:3]
	v_mfma_f32_16x16x32_bf16 v[28:31], v[162:165], v[194:197], v[28:31]
	v_mfma_f32_16x16x32_bf16 v[24:27], v[162:165], v[202:205], v[24:27]
	v_mfma_f32_16x16x32_bf16 v[20:23], v[170:173], v[194:197], v[20:23]
	v_mfma_f32_16x16x32_bf16 v[16:19], v[170:173], v[202:205], v[16:19]
	v_mfma_f32_16x16x32_bf16 v[12:15], v[178:181], v[194:197], v[12:15]
	v_mfma_f32_16x16x32_bf16 v[8:11], v[178:181], v[202:205], v[8:11]
	v_mfma_f32_16x16x32_bf16 v[4:7], v[186:189], v[194:197], v[4:7]
	v_mfma_f32_16x16x32_bf16 v[0:3], v[186:189], v[202:205], v[0:3]
	s_setprio 0
	s_barrier
	ds_read_b128 v[142:145], v139 offset:32768
	ds_read_b128 v[146:149], v139 offset:33792
	ds_read_b128 v[150:153], v139 offset:34816
	ds_read_b128 v[154:157], v139 offset:35840
	s_mov_b32 m0, s29
	v_lshl_add_u64 v[190:191], v[136:137], 0, s[14:15]
	ds_read_b128 v[158:161], v138 offset:32768
	ds_read_b128 v[162:165], v138 offset:33792
	ds_read_b128 v[166:169], v138 offset:34816
	ds_read_b128 v[170:173], v138 offset:35840
	ds_read_b128 v[174:177], v138 offset:36864
	ds_read_b128 v[178:181], v138 offset:37888
	ds_read_b128 v[182:185], v138 offset:38912
	ds_read_b128 v[186:189], v138 offset:39936
	global_load_lds_dwordx4 v[190:191], off
	v_lshl_add_u64 v[190:191], v[136:137], 0, s[16:17]
	s_mov_b32 m0, s33
	s_nop 0
	global_load_lds_dwordx4 v[190:191], off
	s_waitcnt lgkmcnt(8)
	s_barrier
; #define STAGE(P, BASE, br, kt) do { const char* _g = (const char*)((BASE) + (size_t)(br) * K + (size_t)(kt) * G_BK); \
;     _Pragma("unroll") for (int _i = 0; _i < 2; ++_i) { \
;       __builtin_amdgcn_global_load_lds((const unsigned*)(_g + (size_t)_i * 128 * K + sg_off), (unsigned*)((char*)(P) + wid * 1024 + _i * 8192), 16, 0, 0); } } while (0)
; #define LDA(dst, b, h) _Pragma("unroll") for (int m = 0; m < 4; ++m) _Pragma("unroll") for (int k = 0; k < 2; ++k) \
;     dst[m][k] = *reinterpret_cast<const bf16x8*>((const char*)shm + aoff + (((b) * 2 + (h)) * 16384 + m * 2048 + k * 1024))
; #define LDB(dst, b, h) _Pragma("unroll") for (int n = 0; n < 2; ++n) _Pragma("unroll") for (int k = 0; k < 2; ++k) \
;     dst[n][k] = *reinterpret_cast<const bf16x8*>((const char*)shm + boff + (((b) * 2 + (h)) * 16384 + n * 2048 + k * 1024))
; #define MMA(ai, bj, At, Bt_) do { __builtin_amdgcn_s_setprio(1); \
;     _Pragma("unroll") for (int m = 0; m < 4; ++m) _Pragma("unroll") for (int n = 0; n < 2; ++n) _Pragma("unroll") for (int k = 0; k < 2; ++k) \
;       acc[ai][bj][m][n] = mfma16(At[m][k], Bt_[n][k], acc[ai][bj][m][n]); \
;     __builtin_amdgcn_s_setprio(0); } while (0)
; #define WAIT_V(n) asm volatile("s_waitcnt vmcnt(" #n ")" ::: "memory")
; #define WAIT_L(n) asm volatile("s_waitcnt lgkmcnt(" #n ")" ::: "memory")
; #define BAR __builtin_amdgcn_s_barrier()
; #define SCHED __builtin_amdgcn_sched_barrier(0)
; template <class Epi>
; __device__ __forceinline__ void gemm_phase(const bfr* __restrict__ A, int lda, const bfr* __restrict__ Bt, int K,
;                                            int nM, int nN, const Epi& epi, bfr* shm, int wv, int nMfull, int ksplit) {
;     ...
;       WAIT_L(8); BAR; WAIT_L(0); MMA(0, 0, At, B0); BAR; SCHED;
;       LDB(B1, 1, 1); STAGE(SB(1, 0), Bk, bcol, t + 3);
;       BAR; WAIT_L(0); MMA(0, 1, At, B1); BAR;
;       LDA(At, 1, 1); STAGE(SA(1, 0), Ak, brow, t + 3);
;       BAR; WAIT_L(0); MMA(1, 0, At, B0); BAR; SCHED;
;       STAGE(SB(1, 1), Bk, bcol + G_HALF, t + 3);
;       WAIT_V(6); BAR; MMA(1, 1, At, B1); BAR;
;     }
	s_waitcnt lgkmcnt(0)
	s_setprio 1
	s_waitcnt lgkmcnt(0)
	v_mfma_f32_16x16x32_bf16 v[124:127], v[158:161], v[142:145], v[124:127]
	v_mfma_f32_16x16x32_bf16 v[120:123], v[158:161], v[150:153], v[120:123]
	v_mfma_f32_16x16x32_bf16 v[116:119], v[166:169], v[142:145], v[116:119]
	v_mfma_f32_16x16x32_bf16 v[112:115], v[166:169], v[150:153], v[112:115]
	v_mfma_f32_16x16x32_bf16 v[108:111], v[174:177], v[142:145], v[108:111]
	v_mfma_f32_16x16x32_bf16 v[104:107], v[174:177], v[150:153], v[104:107]
	v_mfma_f32_16x16x32_bf16 v[100:103], v[182:185], v[142:145], v[100:103]
	v_mfma_f32_16x16x32_bf16 v[96:99], v[182:185], v[150:153], v[96:99]
	v_mfma_f32_16x16x32_bf16 v[124:127], v[162:165], v[146:149], v[124:127]
	v_mfma_f32_16x16x32_bf16 v[120:123], v[162:165], v[154:157], v[120:123]
	v_mfma_f32_16x16x32_bf16 v[116:119], v[170:173], v[146:149], v[116:119]
	v_mfma_f32_16x16x32_bf16 v[112:115], v[170:173], v[154:157], v[112:115]
	v_mfma_f32_16x16x32_bf16 v[108:111], v[178:181], v[146:149], v[108:111]
	v_mfma_f32_16x16x32_bf16 v[104:107], v[178:181], v[154:157], v[104:107]
	v_mfma_f32_16x16x32_bf16 v[100:103], v[186:189], v[146:149], v[100:103]
	v_mfma_f32_16x16x32_bf16 v[96:99], v[186:189], v[154:157], v[96:99]
	s_setprio 0
	s_barrier
	s_mov_b32 m0, s48
	v_lshl_add_u64 v[208:209], v[206:207], 0, s[18:19]
	ds_read_b128 v[190:193], v139 offset:49152
	ds_read_b128 v[194:197], v139 offset:50176
	ds_read_b128 v[198:201], v139 offset:51200
	ds_read_b128 v[202:205], v139 offset:52224
	global_load_lds_dwordx4 v[208:209], off
	v_lshl_add_u64 v[208:209], v[206:207], 0, s[20:21]
	s_mov_b32 m0, s49
	s_nop 0
	global_load_lds_dwordx4 v[208:209], off
	s_barrier
	s_waitcnt lgkmcnt(0)
	s_setprio 1
	s_waitcnt lgkmcnt(0)
	v_mfma_f32_16x16x32_bf16 v[92:95], v[158:161], v[190:193], v[92:95]
	v_mfma_f32_16x16x32_bf16 v[88:91], v[158:161], v[198:201], v[88:91]
	v_mfma_f32_16x16x32_bf16 v[84:87], v[166:169], v[190:193], v[84:87]
	v_mfma_f32_16x16x32_bf16 v[80:83], v[166:169], v[198:201], v[80:83]
	v_mfma_f32_16x16x32_bf16 v[76:79], v[174:177], v[190:193], v[76:79]
	v_mfma_f32_16x16x32_bf16 v[72:75], v[174:177], v[198:201], v[72:75]
	v_mfma_f32_16x16x32_bf16 v[68:71], v[182:185], v[190:193], v[68:71]
	v_mfma_f32_16x16x32_bf16 v[64:67], v[182:185], v[198:201], v[64:67]
	v_mfma_f32_16x16x32_bf16 v[92:95], v[162:165], v[194:197], v[92:95]
	v_mfma_f32_16x16x32_bf16 v[88:91], v[162:165], v[202:205], v[88:91]
	v_mfma_f32_16x16x32_bf16 v[84:87], v[170:173], v[194:197], v[84:87]
	v_mfma_f32_16x16x32_bf16 v[80:83], v[170:173], v[202:205], v[80:83]
	v_mfma_f32_16x16x32_bf16 v[76:79], v[178:181], v[194:197], v[76:79]
	v_mfma_f32_16x16x32_bf16 v[72:75], v[178:181], v[202:205], v[72:75]
	v_mfma_f32_16x16x32_bf16 v[68:71], v[186:189], v[194:197], v[68:71]
	v_mfma_f32_16x16x32_bf16 v[64:67], v[186:189], v[202:205], v[64:67]
	s_setprio 0
	s_mov_b32 m0, s50
	v_lshl_add_u64 v[208:209], v[136:137], 0, s[18:19]
	s_barrier
	ds_read_b128 v[158:161], v138 offset:49152
	ds_read_b128 v[162:165], v138 offset:50176
	ds_read_b128 v[166:169], v138 offset:51200
	ds_read_b128 v[170:173], v138 offset:52224
	ds_read_b128 v[174:177], v138 offset:53248
	ds_read_b128 v[178:181], v138 offset:54272
	ds_read_b128 v[182:185], v138 offset:55296
	ds_read_b128 v[186:189], v138 offset:56320
	global_load_lds_dwordx4 v[208:209], off
	v_lshl_add_u64 v[136:137], v[136:137], 0, s[20:21]
	s_mov_b32 m0, s51
	s_nop 0
	global_load_lds_dwordx4 v[136:137], off
	s_barrier
	s_waitcnt lgkmcnt(0)
	s_setprio 1
	s_waitcnt lgkmcnt(0)
	v_mfma_f32_16x16x32_bf16 v[60:63], v[158:161], v[142:145], v[60:63]
	v_mfma_f32_16x16x32_bf16 v[56:59], v[158:161], v[150:153], v[56:59]
	v_mfma_f32_16x16x32_bf16 v[52:55], v[166:169], v[142:145], v[52:55]
	v_mfma_f32_16x16x32_bf16 v[48:51], v[166:169], v[150:153], v[48:51]
	v_mfma_f32_16x16x32_bf16 v[44:47], v[174:177], v[142:145], v[44:47]
	v_mfma_f32_16x16x32_bf16 v[40:43], v[174:177], v[150:153], v[40:43]
	v_mfma_f32_16x16x32_bf16 v[36:39], v[182:185], v[142:145], v[36:39]
	v_mfma_f32_16x16x32_bf16 v[32:35], v[182:185], v[150:153], v[32:35]
	v_mfma_f32_16x16x32_bf16 v[60:63], v[162:165], v[146:149], v[60:63]
	v_mfma_f32_16x16x32_bf16 v[56:59], v[162:165], v[154:157], v[56:59]
	v_mfma_f32_16x16x32_bf16 v[52:55], v[170:173], v[146:149], v[52:55]
	v_mfma_f32_16x16x32_bf16 v[48:51], v[170:173], v[154:157], v[48:51]
	v_mfma_f32_16x16x32_bf16 v[44:47], v[178:181], v[146:149], v[44:47]
	v_mfma_f32_16x16x32_bf16 v[40:43], v[178:181], v[154:157], v[40:43]
	v_mfma_f32_16x16x32_bf16 v[36:39], v[186:189], v[146:149], v[36:39]
	v_mfma_f32_16x16x32_bf16 v[32:35], v[186:189], v[154:157], v[32:35]
	s_setprio 0
	s_barrier
	s_mov_b64 s[46:47], 0x40180
	s_mov_b32 m0, s52
	v_lshl_add_u64 v[136:137], v[206:207], 0, s[46:47]
	s_mov_b64 s[46:47], 0x60180
	global_load_lds_dwordx4 v[136:137], off
	v_lshl_add_u64 v[136:137], v[206:207], 0, s[46:47]
	s_mov_b32 m0, s53
	s_nop 0
	global_load_lds_dwordx4 v[136:137], off
	s_waitcnt vmcnt(6)
	s_barrier
	s_setprio 1
	v_mfma_f32_16x16x32_bf16 v[28:31], v[158:161], v[190:193], v[28:31]
	v_mfma_f32_16x16x32_bf16 v[24:27], v[158:161], v[198:201], v[24:27]
	v_mfma_f32_16x16x32_bf16 v[20:23], v[166:169], v[190:193], v[20:23]
	v_mfma_f32_16x16x32_bf16 v[16:19], v[166:169], v[198:201], v[16:19]
	v_mfma_f32_16x16x32_bf16 v[12:15], v[174:177], v[190:193], v[12:15]
	v_mfma_f32_16x16x32_bf16 v[8:11], v[174:177], v[198:201], v[8:11]
	v_mfma_f32_16x16x32_bf16 v[4:7], v[182:185], v[190:193], v[4:7]
	v_mfma_f32_16x16x32_bf16 v[0:3], v[182:185], v[198:201], v[0:3]
	v_mfma_f32_16x16x32_bf16 v[28:31], v[162:165], v[194:197], v[28:31]
	v_mfma_f32_16x16x32_bf16 v[24:27], v[162:165], v[202:205], v[24:27]
	v_mfma_f32_16x16x32_bf16 v[20:23], v[170:173], v[194:197], v[20:23]
	v_mfma_f32_16x16x32_bf16 v[16:19], v[170:173], v[202:205], v[16:19]
	v_mfma_f32_16x16x32_bf16 v[12:15], v[178:181], v[194:197], v[12:15]
	v_mfma_f32_16x16x32_bf16 v[8:11], v[178:181], v[202:205], v[8:11]
	v_mfma_f32_16x16x32_bf16 v[4:7], v[186:189], v[194:197], v[4:7]
	v_mfma_f32_16x16x32_bf16 v[0:3], v[186:189], v[202:205], v[0:3]
	s_setprio 0
	s_add_u32 s36, s36, 0x100
	s_addc_u32 s37, s37, 0
	s_add_u32 s38, s38, 0x100
	s_addc_u32 s39, s39, 0
	s_cmp_ge_i32 s40, s31
	s_barrier
	s_cbranch_scc0 .LBB0_195
; #define STAGE(P, BASE, br, kt) do { const char* _g = (const char*)((BASE) + (size_t)(br) * K + (size_t)(kt) * G_BK); \
;     _Pragma("unroll") for (int _i = 0; _i < 2; ++_i) { \
;       __builtin_amdgcn_global_load_lds((const unsigned*)(_g + (size_t)_i * 128 * K + sg_off), (unsigned*)((char*)(P) + wid * 1024 + _i * 8192), 16, 0, 0); } } while (0)
; #define LDA(dst, b, h) _Pragma("unroll") for (int m = 0; m < 4; ++m) _Pragma("unroll") for (int k = 0; k < 2; ++k) \
;     dst[m][k] = *reinterpret_cast<const bf16x8*>((const char*)shm + aoff + (((b) * 2 + (h)) * 16384 + m * 2048 + k * 1024))
; #define LDB(dst, b, h) _Pragma("unroll") for (int n = 0; n < 2; ++n) _Pragma("unroll") for (int k = 0; k < 2; ++k) \
;     dst[n][k] = *reinterpret_cast<const bf16x8*>((const char*)shm + boff + (((b) * 2 + (h)) * 16384 + n * 2048 + k * 1024))
; #define MMA(ai, bj, At, Bt_) do { __builtin_amdgcn_s_setprio(1); \
;     _Pragma("unroll") for (int m = 0; m < 4; ++m) _Pragma("unroll") for (int n = 0; n < 2; ++n) _Pragma("unroll") for (int k = 0; k < 2; ++k) \
;       acc[ai][bj][m][n] = mfma16(At[m][k], Bt_[n][k], acc[ai][bj][m][n]); \
;     __builtin_amdgcn_s_setprio(0); } while (0)
; #define WAIT_V(n) asm volatile("s_waitcnt vmcnt(" #n ")" ::: "memory")
; #define WAIT_L(n) asm volatile("s_waitcnt lgkmcnt(" #n ")" ::: "memory")
; #define BAR __builtin_amdgcn_s_barrier()
; template <class Epi>
; __device__ __forceinline__ void gemm_phase(const bfr* __restrict__ A, int lda, const bfr* __restrict__ Bt, int K,
;                                            int nM, int nN, const Epi& epi, bfr* shm, int wv, int nMfull, int ksplit) {
;     ...
;     { LDB(B0, 0, 0); LDA(At, 0, 0); STAGE(SA(1, 1), Ak, brow + G_HALF, nt - 1);
;       BAR; WAIT_L(0); MMA(0, 0, At, B0); BAR;
;       LDB(B1, 0, 1); BAR; WAIT_L(0); MMA(0, 1, At, B1); BAR;
;       LDA(At, 0, 1); WAIT_V(4); BAR; WAIT_L(0); MMA(1, 0, At, B0); MMA(1, 1, At, B1); BAR; }
.LBB0_196:
	s_add_i32 s46, s44, 0x80
	s_ashr_i32 s47, s46, 31
	s_lshl_b64 s[36:37], s[46:47], 11
	s_add_u32 s36, s80, s36
	s_addc_u32 s37, s81, s37
	s_ashr_i32 s31, s30, 31
	s_lshl_b64 s[30:31], s[30:31], 7
	s_add_u32 s30, s36, s30
	s_addc_u32 s31, s37, s31
	v_lshl_add_u64 v[136:137], s[30:31], 0, v[128:129]
	s_movk_i32 s30, 0xff80
	s_mov_b32 s31, -1
	s_mov_b32 m0, s54
	v_lshl_add_u64 v[190:191], v[136:137], 0, s[30:31]
	s_mov_b64 s[30:31], 0x1ff80
	ds_read_b128 v[142:145], v139
	ds_read_b128 v[146:149], v139 offset:1024
	ds_read_b128 v[150:153], v139 offset:2048
	ds_read_b128 v[154:157], v139 offset:3072
	ds_read_b128 v[158:161], v138
	ds_read_b128 v[162:165], v138 offset:1024
	ds_read_b128 v[166:169], v138 offset:2048
	ds_read_b128 v[170:173], v138 offset:3072
	ds_read_b128 v[174:177], v138 offset:4096
	ds_read_b128 v[178:181], v138 offset:5120
	ds_read_b128 v[182:185], v138 offset:6144
	ds_read_b128 v[186:189], v138 offset:7168
	global_load_lds_dwordx4 v[190:191], off
	v_lshl_add_u64 v[136:137], v[136:137], 0, s[30:31]
	s_mov_b32 m0, s55
	s_nop 0
	global_load_lds_dwordx4 v[136:137], off
	s_barrier
	s_waitcnt lgkmcnt(0)
	s_setprio 1
	s_waitcnt lgkmcnt(0)
	v_mfma_f32_16x16x32_bf16 v[124:127], v[158:161], v[142:145], v[124:127]
	v_mfma_f32_16x16x32_bf16 v[116:119], v[166:169], v[142:145], v[116:119]
	v_mfma_f32_16x16x32_bf16 v[112:115], v[166:169], v[150:153], v[112:115]
	v_mfma_f32_16x16x32_bf16 v[100:103], v[182:185], v[142:145], v[100:103]
	v_mfma_f32_16x16x32_bf16 v[96:99], v[182:185], v[150:153], v[96:99]
	v_mfma_f32_16x16x32_bf16 v[124:127], v[162:165], v[146:149], v[124:127]
	v_mfma_f32_16x16x32_bf16 v[120:123], v[158:161], v[150:153], v[120:123]
	v_mfma_f32_16x16x32_bf16 v[116:119], v[170:173], v[146:149], v[116:119]
	v_mfma_f32_16x16x32_bf16 v[112:115], v[170:173], v[154:157], v[112:115]
	v_mfma_f32_16x16x32_bf16 v[108:111], v[174:177], v[142:145], v[108:111]
	v_mfma_f32_16x16x32_bf16 v[104:107], v[174:177], v[150:153], v[104:107]
	v_mfma_f32_16x16x32_bf16 v[100:103], v[186:189], v[146:149], v[100:103]
	v_mfma_f32_16x16x32_bf16 v[96:99], v[186:189], v[154:157], v[96:99]
	v_mfma_f32_16x16x32_bf16 v[190:193], v[162:165], v[154:157], v[120:123]
	v_mfma_f32_16x16x32_bf16 v[194:197], v[178:181], v[146:149], v[108:111]
	v_mfma_f32_16x16x32_bf16 v[198:201], v[178:181], v[154:157], v[104:107]
	s_setprio 0
	s_barrier
	s_nop 0
	ds_read_b128 v[104:107], v139 offset:16384
	ds_read_b128 v[108:111], v139 offset:17408
	ds_read_b128 v[120:123], v139 offset:18432
	ds_read_b128 v[202:205], v139 offset:19456
	s_barrier
	s_waitcnt lgkmcnt(0)
	s_setprio 1
	s_waitcnt lgkmcnt(0)
	v_mfma_f32_16x16x32_bf16 v[84:87], v[166:169], v[104:107], v[84:87]
	v_mfma_f32_16x16x32_bf16 v[80:83], v[166:169], v[120:123], v[80:83]
	v_mfma_f32_16x16x32_bf16 v[68:71], v[182:185], v[104:107], v[68:71]
	v_mfma_f32_16x16x32_bf16 v[92:95], v[158:161], v[104:107], v[92:95]
	v_mfma_f32_16x16x32_bf16 v[88:91], v[158:161], v[120:123], v[88:91]
	v_mfma_f32_16x16x32_bf16 v[84:87], v[170:173], v[108:111], v[84:87]
	v_mfma_f32_16x16x32_bf16 v[80:83], v[170:173], v[202:205], v[80:83]
	v_mfma_f32_16x16x32_bf16 v[76:79], v[174:177], v[104:107], v[76:79]
	v_mfma_f32_16x16x32_bf16 v[72:75], v[174:177], v[120:123], v[72:75]
	v_mfma_f32_16x16x32_bf16 v[68:71], v[186:189], v[108:111], v[68:71]
	v_mfma_f32_16x16x32_bf16 v[64:67], v[182:185], v[120:123], v[64:67]
	v_mfma_f32_16x16x32_bf16 v[206:209], v[162:165], v[108:111], v[92:95]
	v_mfma_f32_16x16x32_bf16 v[158:161], v[162:165], v[202:205], v[88:91]
	v_mfma_f32_16x16x32_bf16 v[162:165], v[178:181], v[108:111], v[76:79]
	v_mfma_f32_16x16x32_bf16 v[166:169], v[178:181], v[202:205], v[72:75]
	v_mfma_f32_16x16x32_bf16 v[170:173], v[186:189], v[202:205], v[64:67]
	s_setprio 0
	s_barrier
	s_nop 0
	ds_read_b128 v[64:67], v138 offset:16384
	ds_read_b128 v[72:75], v138 offset:17408
	ds_read_b128 v[76:79], v138 offset:18432
	ds_read_b128 v[88:91], v138 offset:19456
	ds_read_b128 v[92:95], v138 offset:20480
	ds_read_b128 v[174:177], v138 offset:21504
	ds_read_b128 v[178:181], v138 offset:22528
	ds_read_b128 v[182:185], v138 offset:23552
	s_waitcnt vmcnt(4)
	s_barrier
	s_waitcnt lgkmcnt(0)
	s_setprio 1
	s_waitcnt lgkmcnt(0)
	v_mfma_f32_16x16x32_bf16 v[60:63], v[64:67], v[142:145], v[60:63]
	v_mfma_f32_16x16x32_bf16 v[52:55], v[76:79], v[142:145], v[52:55]
	v_mfma_f32_16x16x32_bf16 v[48:51], v[76:79], v[150:153], v[48:51]
	v_mfma_f32_16x16x32_bf16 v[36:39], v[178:181], v[142:145], v[36:39]
	v_mfma_f32_16x16x32_bf16 v[32:35], v[178:181], v[150:153], v[32:35]
	v_mfma_f32_16x16x32_bf16 v[60:63], v[72:75], v[146:149], v[60:63]
	v_mfma_f32_16x16x32_bf16 v[56:59], v[64:67], v[150:153], v[56:59]
	v_mfma_f32_16x16x32_bf16 v[52:55], v[88:91], v[146:149], v[52:55]
	v_mfma_f32_16x16x32_bf16 v[48:51], v[88:91], v[154:157], v[48:51]
	v_mfma_f32_16x16x32_bf16 v[44:47], v[92:95], v[142:145], v[44:47]
	v_mfma_f32_16x16x32_bf16 v[40:43], v[92:95], v[150:153], v[40:43]
	v_mfma_f32_16x16x32_bf16 v[36:39], v[182:185], v[146:149], v[36:39]
	v_mfma_f32_16x16x32_bf16 v[32:35], v[182:185], v[154:157], v[32:35]
	v_mfma_f32_16x16x32_bf16 v[186:189], v[72:75], v[154:157], v[56:59]
	v_mfma_f32_16x16x32_bf16 v[210:213], v[174:177], v[146:149], v[44:47]
	v_mfma_f32_16x16x32_bf16 v[214:217], v[174:177], v[154:157], v[40:43]
	s_setprio 0
	s_setprio 1
	v_mfma_f32_16x16x32_bf16 v[20:23], v[76:79], v[104:107], v[20:23]
	v_mfma_f32_16x16x32_bf16 v[16:19], v[76:79], v[120:123], v[16:19]
	v_mfma_f32_16x16x32_bf16 v[4:7], v[178:181], v[104:107], v[4:7]
	v_mfma_f32_16x16x32_bf16 v[28:31], v[64:67], v[104:107], v[28:31]
	v_mfma_f32_16x16x32_bf16 v[24:27], v[64:67], v[120:123], v[24:27]
	v_mfma_f32_16x16x32_bf16 v[20:23], v[88:91], v[108:111], v[20:23]
	v_mfma_f32_16x16x32_bf16 v[16:19], v[88:91], v[202:205], v[16:19]
	v_mfma_f32_16x16x32_bf16 v[12:15], v[92:95], v[104:107], v[12:15]
	v_mfma_f32_16x16x32_bf16 v[8:11], v[92:95], v[120:123], v[8:11]
	v_mfma_f32_16x16x32_bf16 v[4:7], v[182:185], v[108:111], v[4:7]
	v_mfma_f32_16x16x32_bf16 v[0:3], v[178:181], v[120:123], v[0:3]
	v_mfma_f32_16x16x32_bf16 v[142:145], v[72:75], v[108:111], v[28:31]
	v_mfma_f32_16x16x32_bf16 v[146:149], v[72:75], v[202:205], v[24:27]
	v_mfma_f32_16x16x32_bf16 v[150:153], v[174:177], v[108:111], v[12:15]
	v_mfma_f32_16x16x32_bf16 v[154:157], v[174:177], v[202:205], v[8:11]
	v_mfma_f32_16x16x32_bf16 v[174:177], v[182:185], v[202:205], v[0:3]
	s_setprio 0
	s_barrier
; #define LDA(dst, b, h) _Pragma("unroll") for (int m = 0; m < 4; ++m) _Pragma("unroll") for (int k = 0; k < 2; ++k) \
;     dst[m][k] = *reinterpret_cast<const bf16x8*>((const char*)shm + aoff + (((b) * 2 + (h)) * 16384 + m * 2048 + k * 1024))
; #define LDB(dst, b, h) _Pragma("unroll") for (int n = 0; n < 2; ++n) _Pragma("unroll") for (int k = 0; k < 2; ++k) \
;     dst[n][k] = *reinterpret_cast<const bf16x8*>((const char*)shm + boff + (((b) * 2 + (h)) * 16384 + n * 2048 + k * 1024))
; #define MMA(ai, bj, At, Bt_) do { __builtin_amdgcn_s_setprio(1); \
;     _Pragma("unroll") for (int m = 0; m < 4; ++m) _Pragma("unroll") for (int n = 0; n < 2; ++n) _Pragma("unroll") for (int k = 0; k < 2; ++k) \
;       acc[ai][bj][m][n] = mfma16(At[m][k], Bt_[n][k], acc[ai][bj][m][n]); \
;     __builtin_amdgcn_s_setprio(0); } while (0)
; #define WAIT_V(n) asm volatile("s_waitcnt vmcnt(" #n ")" ::: "memory")
; #define WAIT_L(n) asm volatile("s_waitcnt lgkmcnt(" #n ")" ::: "memory")
; #define BAR __builtin_amdgcn_s_barrier()
; template <class Epi>
; __device__ __forceinline__ void gemm_phase(const bfr* __restrict__ A, int lda, const bfr* __restrict__ Bt, int K,
;                                            int nM, int nN, const Epi& epi, bfr* shm, int wv, int nMfull, int ksplit) {
;     ...
;     { LDB(B0, 1, 0); LDA(At, 1, 0); WAIT_V(2); BAR; WAIT_L(0); MMA(0, 0, At, B0); BAR;
;       LDB(B1, 1, 1); WAIT_V(0); BAR; WAIT_L(0); MMA(0, 1, At, B1); BAR;
;       LDA(At, 1, 1); BAR; WAIT_L(0); MMA(1, 0, At, B0); MMA(1, 1, At, B1); BAR; }
;     if (wr == 0) BAR;
	s_nop 0
	ds_read_b128 v[0:3], v139 offset:32768
	ds_read_b128 v[8:11], v139 offset:33792
	ds_read_b128 v[12:15], v139 offset:34816
	ds_read_b128 v[178:181], v139 offset:35840
	ds_read_b128 v[24:27], v138 offset:32768
	ds_read_b128 v[28:31], v138 offset:33792
	ds_read_b128 v[40:43], v138 offset:34816
	ds_read_b128 v[44:47], v138 offset:35840
	ds_read_b128 v[56:59], v138 offset:36864
	ds_read_b128 v[64:67], v138 offset:37888
	ds_read_b128 v[182:185], v138 offset:38912
	ds_read_b128 v[202:205], v138 offset:39936
	s_waitcnt vmcnt(2)
	s_barrier
	s_waitcnt lgkmcnt(0)
	s_setprio 1
	s_waitcnt lgkmcnt(0)
	v_mfma_f32_16x16x32_bf16 v[72:75], v[24:27], v[0:3], v[124:127]
	v_mfma_f32_16x16x32_bf16 v[120:123], v[28:31], v[8:11], v[72:75]
	v_mfma_f32_16x16x32_bf16 v[72:75], v[24:27], v[12:15], v[190:193]
	v_mfma_f32_16x16x32_bf16 v[124:127], v[28:31], v[178:181], v[72:75]
	v_mfma_f32_16x16x32_bf16 v[72:75], v[40:43], v[0:3], v[116:119]
	v_mfma_f32_16x16x32_bf16 v[104:107], v[44:47], v[8:11], v[72:75]
	v_mfma_f32_16x16x32_bf16 v[72:75], v[40:43], v[12:15], v[112:115]
	v_mfma_f32_16x16x32_bf16 v[108:111], v[44:47], v[178:181], v[72:75]
	v_mfma_f32_16x16x32_bf16 v[72:75], v[56:59], v[0:3], v[194:197]
	v_mfma_f32_16x16x32_bf16 v[88:91], v[64:67], v[8:11], v[72:75]
	v_mfma_f32_16x16x32_bf16 v[72:75], v[56:59], v[12:15], v[198:201]
	v_mfma_f32_16x16x32_bf16 v[92:95], v[64:67], v[178:181], v[72:75]
	v_mfma_f32_16x16x32_bf16 v[72:75], v[182:185], v[0:3], v[100:103]
	v_mfma_f32_16x16x32_bf16 v[76:79], v[182:185], v[12:15], v[96:99]
	v_mfma_f32_16x16x32_bf16 v[72:75], v[202:205], v[8:11], v[72:75]
	v_mfma_f32_16x16x32_bf16 v[76:79], v[202:205], v[178:181], v[76:79]
	s_setprio 0
	s_barrier
	ds_read_b128 v[190:193], v139 offset:49152
	ds_read_b128 v[194:197], v139 offset:50176
	ds_read_b128 v[198:201], v139 offset:51200
	ds_read_b128 v[218:221], v139 offset:52224
	s_waitcnt vmcnt(0)
	s_barrier
	s_waitcnt lgkmcnt(0)
	s_setprio 1
	s_waitcnt lgkmcnt(0)
	v_mfma_f32_16x16x32_bf16 v[96:99], v[24:27], v[190:193], v[206:209]
	v_mfma_f32_16x16x32_bf16 v[24:27], v[24:27], v[198:201], v[158:161]
	v_mfma_f32_16x16x32_bf16 v[116:119], v[28:31], v[218:221], v[24:27]
	v_mfma_f32_16x16x32_bf16 v[24:27], v[40:43], v[190:193], v[84:87]
	v_mfma_f32_16x16x32_bf16 v[112:115], v[28:31], v[194:197], v[96:99]
	v_mfma_f32_16x16x32_bf16 v[96:99], v[44:47], v[194:197], v[24:27]
	v_mfma_f32_16x16x32_bf16 v[24:27], v[40:43], v[198:201], v[80:83]
	v_mfma_f32_16x16x32_bf16 v[100:103], v[44:47], v[218:221], v[24:27]
	v_mfma_f32_16x16x32_bf16 v[24:27], v[56:59], v[190:193], v[162:165]
	v_mfma_f32_16x16x32_bf16 v[80:83], v[64:67], v[194:197], v[24:27]
	v_mfma_f32_16x16x32_bf16 v[24:27], v[56:59], v[198:201], v[166:169]
	v_mfma_f32_16x16x32_bf16 v[84:87], v[64:67], v[218:221], v[24:27]
	v_mfma_f32_16x16x32_bf16 v[24:27], v[182:185], v[190:193], v[68:71]
	v_mfma_f32_16x16x32_bf16 v[64:67], v[202:205], v[194:197], v[24:27]
	v_mfma_f32_16x16x32_bf16 v[24:27], v[182:185], v[198:201], v[170:173]
	v_mfma_f32_16x16x32_bf16 v[68:71], v[202:205], v[218:221], v[24:27]
	s_setprio 0
	s_barrier
	ds_read_b128 v[158:161], v138 offset:49152
	ds_read_b128 v[162:165], v138 offset:50176
	ds_read_b128 v[166:169], v138 offset:51200
	ds_read_b128 v[170:173], v138 offset:52224
	ds_read_b128 v[182:185], v138 offset:53248
	ds_read_b128 v[202:205], v138 offset:54272
	ds_read_b128 v[206:209], v138 offset:55296
	ds_read_b128 v[222:225], v138 offset:56320
	s_barrier
	s_waitcnt lgkmcnt(0)
	s_setprio 1
	s_waitcnt lgkmcnt(0)
	v_mfma_f32_16x16x32_bf16 v[24:27], v[158:161], v[0:3], v[60:63]
	v_mfma_f32_16x16x32_bf16 v[56:59], v[162:165], v[8:11], v[24:27]
	v_mfma_f32_16x16x32_bf16 v[24:27], v[158:161], v[12:15], v[186:189]
	v_mfma_f32_16x16x32_bf16 v[60:63], v[162:165], v[178:181], v[24:27]
	v_mfma_f32_16x16x32_bf16 v[24:27], v[166:169], v[0:3], v[52:55]
	v_mfma_f32_16x16x32_bf16 v[40:43], v[170:173], v[8:11], v[24:27]
	v_mfma_f32_16x16x32_bf16 v[24:27], v[166:169], v[12:15], v[48:51]
	v_mfma_f32_16x16x32_bf16 v[44:47], v[170:173], v[178:181], v[24:27]
	v_mfma_f32_16x16x32_bf16 v[24:27], v[182:185], v[0:3], v[210:213]
	v_mfma_f32_16x16x32_bf16 v[0:3], v[206:209], v[0:3], v[36:39]
	v_mfma_f32_16x16x32_bf16 v[24:27], v[202:205], v[8:11], v[24:27]
	v_mfma_f32_16x16x32_bf16 v[28:31], v[182:185], v[12:15], v[214:217]
	v_mfma_f32_16x16x32_bf16 v[8:11], v[222:225], v[8:11], v[0:3]
	v_mfma_f32_16x16x32_bf16 v[0:3], v[206:209], v[12:15], v[32:35]
	v_mfma_f32_16x16x32_bf16 v[28:31], v[202:205], v[178:181], v[28:31]
	v_mfma_f32_16x16x32_bf16 v[12:15], v[222:225], v[178:181], v[0:3]
	s_setprio 0
	s_setprio 1
	v_mfma_f32_16x16x32_bf16 v[0:3], v[158:161], v[190:193], v[142:145]
	v_mfma_f32_16x16x32_bf16 v[48:51], v[162:165], v[194:197], v[0:3]
	v_mfma_f32_16x16x32_bf16 v[0:3], v[158:161], v[198:201], v[146:149]
	v_mfma_f32_16x16x32_bf16 v[52:55], v[162:165], v[218:221], v[0:3]
	v_mfma_f32_16x16x32_bf16 v[0:3], v[166:169], v[190:193], v[20:23]
	v_mfma_f32_16x16x32_bf16 v[32:35], v[170:173], v[194:197], v[0:3]
	v_mfma_f32_16x16x32_bf16 v[0:3], v[166:169], v[198:201], v[16:19]
	v_mfma_f32_16x16x32_bf16 v[36:39], v[170:173], v[218:221], v[0:3]
	v_mfma_f32_16x16x32_bf16 v[0:3], v[182:185], v[190:193], v[150:153]
	v_mfma_f32_16x16x32_bf16 v[16:19], v[202:205], v[194:197], v[0:3]
	v_mfma_f32_16x16x32_bf16 v[0:3], v[182:185], v[198:201], v[154:157]
	v_mfma_f32_16x16x32_bf16 v[20:23], v[202:205], v[218:221], v[0:3]
	v_mfma_f32_16x16x32_bf16 v[0:3], v[206:209], v[190:193], v[4:7]
	v_mfma_f32_16x16x32_bf16 v[4:7], v[206:209], v[198:201], v[174:177]
	v_mfma_f32_16x16x32_bf16 v[0:3], v[222:225], v[194:197], v[0:3]
	v_mfma_f32_16x16x32_bf16 v[4:7], v[222:225], v[218:221], v[4:7]
	s_setprio 0
	s_and_b64 vcc, exec, s[8:9]
	s_barrier
	s_cbranch_vccz .LBB0_198
	s_barrier

; #define WAIT_V(n) asm volatile("s_waitcnt vmcnt(" #n ")" ::: "memory")
; #define BAR __builtin_amdgcn_s_barrier()
; template <class Epi>
; __device__ __forceinline__ void gemm_phase(const bfr* __restrict__ A, int lda, const bfr* __restrict__ Bt, int K,
;                                            int nM, int nN, const Epi& epi, bfr* shm, int wv, int nMfull, int ksplit) {
;     ...
;   while (item < nitems) {
;     const bfr* Ak = A + kbeg; const bfr* Bk = Bt + kbeg;
;     f32x4 acc[2][2][4][2];
; #pragma unroll
;     for (int a = 0; a < 2; a++)
; #pragma unroll
;       for (int b = 0; b < 2; b++)
; #pragma unroll
;         for (int m = 0; m < 4; m++)
; #pragma unroll
;           for (int n = 0; n < 2; n++) acc[a][b][m][n] = f32x4{0.f, 0.f, 0.f, 0.f};
;     bf16x8 At[4][2], B0[2][2], B1[2][2];
;     if (wr == 1) BAR;
;     WAIT_V(10); BAR;
;     WAIT_V(6); BAR;
;     for (int t = 0; t < nt - 2; t += 2) {
.LBB0_240:
	s_lshl_b64 s[38:39], s[6:7], 1
	s_add_u32 s4, s82, s38
	s_waitcnt vmcnt(10)
	s_barrier
	s_waitcnt vmcnt(6)
	s_addc_u32 s5, s83, s39
	v_mov_b32_e32 v127, 0
	s_cmp_lt_u32 s96, 3
	v_mov_b32_e32 v126, v127
	v_mov_b32_e32 v125, v127
	v_mov_b32_e32 v124, v127
	v_mov_b32_e32 v123, v127
	v_mov_b32_e32 v122, v127
	v_mov_b32_e32 v121, v127
	v_mov_b32_e32 v120, v127
	v_mov_b32_e32 v119, v127
	v_mov_b32_e32 v118, v127
	v_mov_b32_e32 v117, v127
	v_mov_b32_e32 v116, v127
	v_mov_b32_e32 v115, v127
	v_mov_b32_e32 v114, v127
	v_mov_b32_e32 v113, v127
	v_mov_b32_e32 v112, v127
	v_mov_b32_e32 v111, v127
	v_mov_b32_e32 v110, v127
	v_mov_b32_e32 v109, v127
	v_mov_b32_e32 v108, v127
	v_mov_b32_e32 v107, v127
	v_mov_b32_e32 v106, v127
	v_mov_b32_e32 v105, v127
	v_mov_b32_e32 v104, v127
	v_mov_b32_e32 v103, v127
	v_mov_b32_e32 v102, v127
	v_mov_b32_e32 v101, v127
	v_mov_b32_e32 v100, v127
	v_mov_b32_e32 v99, v127
	v_mov_b32_e32 v98, v127
	v_mov_b32_e32 v97, v127
	v_mov_b32_e32 v96, v127
	v_mov_b32_e32 v95, v127
	v_mov_b32_e32 v94, v127
	v_mov_b32_e32 v93, v127
	v_mov_b32_e32 v92, v127
	v_mov_b32_e32 v91, v127
	v_mov_b32_e32 v90, v127
	v_mov_b32_e32 v89, v127
	v_mov_b32_e32 v88, v127
	v_mov_b32_e32 v87, v127
	v_mov_b32_e32 v86, v127
	v_mov_b32_e32 v85, v127
	v_mov_b32_e32 v84, v127
	v_mov_b32_e32 v83, v127
	v_mov_b32_e32 v82, v127
	v_mov_b32_e32 v81, v127
	v_mov_b32_e32 v80, v127
	v_mov_b32_e32 v79, v127
	v_mov_b32_e32 v78, v127
	v_mov_b32_e32 v77, v127
	v_mov_b32_e32 v76, v127
	v_mov_b32_e32 v75, v127
	v_mov_b32_e32 v74, v127
	v_mov_b32_e32 v73, v127
	v_mov_b32_e32 v72, v127
	v_mov_b32_e32 v71, v127
	v_mov_b32_e32 v70, v127
	v_mov_b32_e32 v69, v127
	v_mov_b32_e32 v68, v127
	v_mov_b32_e32 v67, v127
	v_mov_b32_e32 v66, v127
	v_mov_b32_e32 v65, v127
	v_mov_b32_e32 v64, v127
	v_mov_b32_e32 v63, v127
	v_mov_b32_e32 v62, v127
	v_mov_b32_e32 v61, v127
	v_mov_b32_e32 v60, v127
	v_mov_b32_e32 v59, v127
	v_mov_b32_e32 v58, v127
	v_mov_b32_e32 v57, v127
	v_mov_b32_e32 v56, v127
	v_mov_b32_e32 v55, v127
	v_mov_b32_e32 v54, v127
	v_mov_b32_e32 v53, v127
	v_mov_b32_e32 v52, v127
	v_mov_b32_e32 v51, v127
	v_mov_b32_e32 v50, v127
	v_mov_b32_e32 v49, v127
	v_mov_b32_e32 v48, v127
	v_mov_b32_e32 v47, v127
	v_mov_b32_e32 v46, v127
	v_mov_b32_e32 v45, v127
	v_mov_b32_e32 v44, v127
	v_mov_b32_e32 v43, v127
	v_mov_b32_e32 v42, v127
	v_mov_b32_e32 v41, v127
	v_mov_b32_e32 v40, v127
	v_mov_b32_e32 v39, v127
	v_mov_b32_e32 v38, v127
	v_mov_b32_e32 v37, v127
	v_mov_b32_e32 v36, v127
	v_mov_b32_e32 v35, v127
	v_mov_b32_e32 v34, v127
	v_mov_b32_e32 v33, v127
	v_mov_b32_e32 v32, v127
	v_mov_b32_e32 v31, v127
	v_mov_b32_e32 v30, v127
	v_mov_b32_e32 v29, v127
	v_mov_b32_e32 v28, v127
	v_mov_b32_e32 v27, v127
	v_mov_b32_e32 v26, v127
	v_mov_b32_e32 v25, v127
	v_mov_b32_e32 v24, v127
	v_mov_b32_e32 v23, v127
	v_mov_b32_e32 v22, v127
	v_mov_b32_e32 v21, v127
	v_mov_b32_e32 v20, v127
	v_mov_b32_e32 v19, v127
	v_mov_b32_e32 v18, v127
	v_mov_b32_e32 v17, v127
	v_mov_b32_e32 v16, v127
	v_mov_b32_e32 v15, v127
	v_mov_b32_e32 v14, v127
	v_mov_b32_e32 v13, v127
	v_mov_b32_e32 v12, v127
	v_mov_b32_e32 v11, v127
	v_mov_b32_e32 v10, v127
	v_mov_b32_e32 v9, v127
	v_mov_b32_e32 v8, v127
	v_mov_b32_e32 v7, v127
	v_mov_b32_e32 v6, v127
	v_mov_b32_e32 v5, v127
	v_mov_b32_e32 v4, v127
	v_mov_b32_e32 v3, v127
	v_mov_b32_e32 v2, v127
	v_mov_b32_e32 v1, v127
	v_mov_b32_e32 v0, v127
	s_barrier
	s_cbranch_scc1 .LBB0_243
	v_readlane_b32 s56, v254, 54
	s_add_i32 s6, s96, -2
	v_readlane_b32 s60, v254, 58
	v_readlane_b32 s61, v254, 59
	s_add_u32 s27, s60, s38
	s_mul_i32 s38, s36, 0xb00
	s_addc_u32 s37, s61, s39
	s_ashr_i32 s39, s38, 31
	s_lshl_b64 s[38:39], s[38:39], 1
	s_add_u32 s38, s27, s38
	s_addc_u32 s39, s37, s39
	s_mul_i32 s37, s13, 0x1600
	s_mul_hi_i32 s27, s13, 0x1600
	s_add_u32 s44, s4, s37
	v_mov_b32_e32 v0, 0
	s_addc_u32 s45, s5, s27
	s_mov_b32 s27, 0
	v_readlane_b32 s57, v254, 55
	v_readlane_b32 s58, v254, 56
	v_readlane_b32 s59, v254, 57
	v_readlane_b32 s62, v254, 60
	v_readlane_b32 s63, v254, 61
	v_readlane_b32 s64, v254, 62
	v_readlane_b32 s65, v254, 63
	v_readlane_b32 s66, v255, 0
	v_readlane_b32 s67, v255, 1
	v_readlane_b32 s68, v255, 2
	v_readlane_b32 s69, v255, 3
	v_readlane_b32 s70, v255, 4
	v_readlane_b32 s71, v255, 5

; #define WAIT_V(n) asm volatile("s_waitcnt vmcnt(" #n ")" ::: "memory")
; #define BAR __builtin_amdgcn_s_barrier()
; template <class Epi>
; __device__ __forceinline__ void gemm_phase(const bfr* __restrict__ A, int lda, const bfr* __restrict__ Bt, int K,
;                                            int nM, int nN, const Epi& epi, bfr* shm, int wv, int nMfull, int ksplit) {
;     ...
;   while (item < nitems) {
;     const bfr* Ak = A + kbeg; const bfr* Bk = Bt + kbeg;
;     f32x4 acc[2][2][4][2];
; #pragma unroll
;     for (int a = 0; a < 2; a++)
; #pragma unroll
;       for (int b = 0; b < 2; b++)
; #pragma unroll
;         for (int m = 0; m < 4; m++)
; #pragma unroll
;           for (int n = 0; n < 2; n++) acc[a][b][m][n] = f32x4{0.f, 0.f, 0.f, 0.f};
;     bf16x8 At[4][2], B0[2][2], B1[2][2];
;     if (wr == 1) BAR;
;     WAIT_V(10); BAR;
;     WAIT_V(6); BAR;
;     for (int t = 0; t < nt - 2; t += 2) {
.LBB0_394:
	s_waitcnt vmcnt(10)
	s_barrier
	s_waitcnt vmcnt(6)
	v_mov_b32_e32 v127, 0
	s_cmp_lt_u32 s0, 3
	v_mov_b32_e32 v126, v127
	v_mov_b32_e32 v125, v127
	v_mov_b32_e32 v124, v127
	v_mov_b32_e32 v123, v127
	v_mov_b32_e32 v122, v127
	v_mov_b32_e32 v121, v127
	v_mov_b32_e32 v120, v127
	v_mov_b32_e32 v119, v127
	v_mov_b32_e32 v118, v127
	v_mov_b32_e32 v117, v127
	v_mov_b32_e32 v116, v127
	v_mov_b32_e32 v115, v127
	v_mov_b32_e32 v114, v127
	v_mov_b32_e32 v113, v127
	v_mov_b32_e32 v112, v127
	v_mov_b32_e32 v111, v127
	v_mov_b32_e32 v110, v127
	v_mov_b32_e32 v109, v127
	v_mov_b32_e32 v108, v127
	v_mov_b32_e32 v107, v127
	v_mov_b32_e32 v106, v127
	v_mov_b32_e32 v105, v127
	v_mov_b32_e32 v104, v127
	v_mov_b32_e32 v103, v127
	v_mov_b32_e32 v102, v127
	v_mov_b32_e32 v101, v127
	v_mov_b32_e32 v100, v127
	v_mov_b32_e32 v99, v127
	v_mov_b32_e32 v98, v127
	v_mov_b32_e32 v97, v127
	v_mov_b32_e32 v96, v127
	v_mov_b32_e32 v95, v127
	v_mov_b32_e32 v94, v127
	v_mov_b32_e32 v93, v127
	v_mov_b32_e32 v92, v127
	v_mov_b32_e32 v91, v127
	v_mov_b32_e32 v90, v127
	v_mov_b32_e32 v89, v127
	v_mov_b32_e32 v88, v127
	v_mov_b32_e32 v87, v127
	v_mov_b32_e32 v86, v127
	v_mov_b32_e32 v85, v127
	v_mov_b32_e32 v84, v127
	v_mov_b32_e32 v83, v127
	v_mov_b32_e32 v82, v127
	v_mov_b32_e32 v81, v127
	v_mov_b32_e32 v80, v127
	v_mov_b32_e32 v79, v127
	v_mov_b32_e32 v78, v127
	v_mov_b32_e32 v77, v127
	v_mov_b32_e32 v76, v127
	v_mov_b32_e32 v75, v127
	v_mov_b32_e32 v74, v127
	v_mov_b32_e32 v73, v127
	v_mov_b32_e32 v72, v127
	v_mov_b32_e32 v71, v127
	v_mov_b32_e32 v70, v127
	v_mov_b32_e32 v69, v127
	v_mov_b32_e32 v68, v127
	v_mov_b32_e32 v67, v127
	v_mov_b32_e32 v66, v127
	v_mov_b32_e32 v65, v127
	v_mov_b32_e32 v64, v127
	v_mov_b32_e32 v63, v127
	v_mov_b32_e32 v62, v127
	v_mov_b32_e32 v61, v127
	v_mov_b32_e32 v60, v127
	v_mov_b32_e32 v59, v127
	v_mov_b32_e32 v58, v127
	v_mov_b32_e32 v57, v127
	v_mov_b32_e32 v56, v127
	v_mov_b32_e32 v55, v127
	v_mov_b32_e32 v54, v127
	v_mov_b32_e32 v53, v127
	v_mov_b32_e32 v52, v127
	v_mov_b32_e32 v51, v127
	v_mov_b32_e32 v50, v127
	v_mov_b32_e32 v49, v127
	v_mov_b32_e32 v48, v127
	v_mov_b32_e32 v47, v127
	v_mov_b32_e32 v46, v127
	v_mov_b32_e32 v45, v127
	v_mov_b32_e32 v44, v127
	v_mov_b32_e32 v43, v127
	v_mov_b32_e32 v42, v127
	v_mov_b32_e32 v41, v127
	v_mov_b32_e32 v40, v127
	v_mov_b32_e32 v39, v127
	v_mov_b32_e32 v38, v127
	v_mov_b32_e32 v37, v127
	v_mov_b32_e32 v36, v127
	v_mov_b32_e32 v35, v127
	v_mov_b32_e32 v34, v127
	v_mov_b32_e32 v33, v127
	v_mov_b32_e32 v32, v127
	v_mov_b32_e32 v31, v127
	v_mov_b32_e32 v30, v127
	v_mov_b32_e32 v29, v127
	v_mov_b32_e32 v28, v127
	v_mov_b32_e32 v27, v127
	v_mov_b32_e32 v26, v127
	v_mov_b32_e32 v25, v127
	v_mov_b32_e32 v24, v127
	v_mov_b32_e32 v23, v127
	v_mov_b32_e32 v22, v127
	v_mov_b32_e32 v21, v127
	v_mov_b32_e32 v20, v127
	v_mov_b32_e32 v19, v127
	v_mov_b32_e32 v18, v127
	v_mov_b32_e32 v17, v127
	v_mov_b32_e32 v16, v127
	v_mov_b32_e32 v15, v127
	v_mov_b32_e32 v14, v127
	v_mov_b32_e32 v13, v127
	v_mov_b32_e32 v12, v127
	v_mov_b32_e32 v11, v127
	v_mov_b32_e32 v10, v127
	v_mov_b32_e32 v9, v127
	v_mov_b32_e32 v8, v127
	v_mov_b32_e32 v7, v127
	v_mov_b32_e32 v6, v127
	v_mov_b32_e32 v5, v127
	v_mov_b32_e32 v4, v127
	v_mov_b32_e32 v3, v127
	v_mov_b32_e32 v2, v127
	v_mov_b32_e32 v1, v127
	v_mov_b32_e32 v0, v127
	s_barrier
	s_cbranch_scc1 .LBB0_398
	s_ashr_i32 s49, s48, 31
	s_ashr_i32 s43, s42, 31
	v_readlane_b32 s60, v254, 54
	s_add_i32 s1, s0, -2
	s_lshl_b64 s[2:3], s[48:49], 11
	s_lshl_b64 s[4:5], s[42:43], 11
	v_readlane_b32 s66, v254, 60
	v_readlane_b32 s67, v254, 61
	s_add_u32 s2, s66, s2
	s_addc_u32 s3, s67, s3
	s_add_u32 s4, s80, s4
	v_mov_b32_e32 v0, 0
	s_addc_u32 s5, s81, s5
	s_mov_b32 s6, 0
	v_readlane_b32 s61, v254, 55
	v_readlane_b32 s62, v254, 56
	v_readlane_b32 s63, v254, 57
	v_readlane_b32 s64, v254, 58
	v_readlane_b32 s65, v254, 59
	v_readlane_b32 s68, v254, 62
	v_readlane_b32 s69, v254, 63
	v_readlane_b32 s70, v255, 0
	v_readlane_b32 s71, v255, 1
	v_readlane_b32 s72, v255, 2
	v_readlane_b32 s73, v255, 3
	v_readlane_b32 s74, v255, 4
	v_readlane_b32 s75, v255, 5

; #define WAIT_V(n) asm volatile("s_waitcnt vmcnt(" #n ")" ::: "memory")
; #define BAR __builtin_amdgcn_s_barrier()
; template <class Epi>
; __device__ __forceinline__ void gemm_phase(const bfr* __restrict__ A, int lda, const bfr* __restrict__ Bt, int K,
;                                            int nM, int nN, const Epi& epi, bfr* shm, int wv, int nMfull, int ksplit) {
;     ...
;   while (item < nitems) {
;     const bfr* Ak = A + kbeg; const bfr* Bk = Bt + kbeg;
;     f32x4 acc[2][2][4][2];
; #pragma unroll
;     for (int a = 0; a < 2; a++)
; #pragma unroll
;       for (int b = 0; b < 2; b++)
; #pragma unroll
;         for (int m = 0; m < 4; m++)
; #pragma unroll
;           for (int n = 0; n < 2; n++) acc[a][b][m][n] = f32x4{0.f, 0.f, 0.f, 0.f};
;     bf16x8 At[4][2], B0[2][2], B1[2][2];
;     if (wr == 1) BAR;
;     WAIT_V(10); BAR;
;     WAIT_V(6); BAR;
;     for (int t = 0; t < nt - 2; t += 2) {
.LBB0_521:
	v_readlane_b32 s52, v255, 10
	s_lshl_b64 s[42:43], s[8:9], 1
	v_readlane_b32 s60, v255, 18
	v_readlane_b32 s61, v255, 19
	s_add_u32 s8, s60, s42
	s_waitcnt vmcnt(10)
	s_barrier
	s_waitcnt vmcnt(6)
	s_addc_u32 s39, s61, s43
	v_mov_b32_e32 v127, 0
	s_cmp_lt_u32 s38, 3
	v_mov_b32_e32 v126, v127
	v_mov_b32_e32 v125, v127
	v_mov_b32_e32 v124, v127
	v_mov_b32_e32 v123, v127
	v_mov_b32_e32 v122, v127
	v_mov_b32_e32 v121, v127
	v_mov_b32_e32 v120, v127
	v_mov_b32_e32 v119, v127
	v_mov_b32_e32 v118, v127
	v_mov_b32_e32 v117, v127
	v_mov_b32_e32 v116, v127
	v_mov_b32_e32 v115, v127
	v_mov_b32_e32 v114, v127
	v_mov_b32_e32 v113, v127
	v_mov_b32_e32 v112, v127
	v_mov_b32_e32 v111, v127
	v_mov_b32_e32 v110, v127
	v_mov_b32_e32 v109, v127
	v_mov_b32_e32 v108, v127
	v_mov_b32_e32 v107, v127
	v_mov_b32_e32 v106, v127
	v_mov_b32_e32 v105, v127
	v_mov_b32_e32 v104, v127
	v_mov_b32_e32 v103, v127
	v_mov_b32_e32 v102, v127
	v_mov_b32_e32 v101, v127
	v_mov_b32_e32 v100, v127
	v_mov_b32_e32 v99, v127
	v_mov_b32_e32 v98, v127
	v_mov_b32_e32 v97, v127
	v_mov_b32_e32 v96, v127
	s_waitcnt vmcnt(0)
	v_mov_b32_e32 v95, v127
	v_mov_b32_e32 v94, v127
	v_mov_b32_e32 v93, v127
	v_mov_b32_e32 v92, v127
	v_mov_b32_e32 v91, v127
	v_mov_b32_e32 v90, v127
	v_mov_b32_e32 v89, v127
	v_mov_b32_e32 v88, v127
	v_mov_b32_e32 v87, v127
	v_mov_b32_e32 v86, v127
	v_mov_b32_e32 v85, v127
	v_mov_b32_e32 v84, v127
	v_mov_b32_e32 v83, v127
	v_mov_b32_e32 v82, v127
	v_mov_b32_e32 v81, v127
	v_mov_b32_e32 v80, v127
	v_mov_b32_e32 v79, v127
	v_mov_b32_e32 v78, v127
	v_mov_b32_e32 v77, v127
	v_mov_b32_e32 v76, v127
	v_mov_b32_e32 v75, v127
	v_mov_b32_e32 v74, v127
	v_mov_b32_e32 v73, v127
	v_mov_b32_e32 v72, v127
	v_mov_b32_e32 v71, v127
	v_mov_b32_e32 v70, v127
	v_mov_b32_e32 v69, v127
	v_mov_b32_e32 v68, v127
	v_mov_b32_e32 v67, v127
	v_mov_b32_e32 v66, v127
	v_mov_b32_e32 v65, v127
	v_mov_b32_e32 v64, v127
	v_mov_b32_e32 v63, v127
	v_mov_b32_e32 v62, v127
	v_mov_b32_e32 v61, v127
	v_mov_b32_e32 v60, v127
	v_mov_b32_e32 v59, v127
	v_mov_b32_e32 v58, v127
	v_mov_b32_e32 v57, v127
	v_mov_b32_e32 v56, v127
	v_mov_b32_e32 v55, v127
	v_mov_b32_e32 v54, v127
	v_mov_b32_e32 v53, v127
	v_mov_b32_e32 v52, v127
	v_mov_b32_e32 v51, v127
	v_mov_b32_e32 v50, v127
	v_mov_b32_e32 v49, v127
	v_mov_b32_e32 v48, v127
	v_mov_b32_e32 v47, v127
	v_mov_b32_e32 v46, v127
	v_mov_b32_e32 v45, v127
	v_mov_b32_e32 v44, v127
	v_mov_b32_e32 v43, v127
	v_mov_b32_e32 v42, v127
	v_mov_b32_e32 v41, v127
	v_mov_b32_e32 v40, v127
	v_mov_b32_e32 v39, v127
	v_mov_b32_e32 v38, v127
	v_mov_b32_e32 v37, v127
	v_mov_b32_e32 v36, v127
	v_mov_b32_e32 v35, v127
	v_mov_b32_e32 v34, v127
	v_mov_b32_e32 v33, v127
	v_mov_b32_e32 v32, v127
	v_mov_b32_e32 v31, v127
	v_mov_b32_e32 v30, v127
	v_mov_b32_e32 v29, v127
	v_mov_b32_e32 v28, v127
	v_mov_b32_e32 v27, v127
	v_mov_b32_e32 v26, v127
	v_mov_b32_e32 v25, v127
	v_mov_b32_e32 v24, v127
	v_mov_b32_e32 v23, v127
	v_mov_b32_e32 v22, v127
	v_mov_b32_e32 v21, v127
	v_mov_b32_e32 v20, v127
	v_mov_b32_e32 v19, v127
	v_mov_b32_e32 v18, v127
	v_mov_b32_e32 v17, v127
	v_mov_b32_e32 v16, v127
	v_mov_b32_e32 v15, v127
	v_mov_b32_e32 v14, v127
	v_mov_b32_e32 v13, v127
	v_mov_b32_e32 v12, v127
	v_mov_b32_e32 v11, v127
	v_mov_b32_e32 v10, v127
	v_mov_b32_e32 v9, v127
	v_mov_b32_e32 v8, v127
	v_mov_b32_e32 v7, v127
	v_mov_b32_e32 v6, v127
	v_mov_b32_e32 v5, v127
	v_mov_b32_e32 v4, v127
	v_mov_b32_e32 v3, v127
	v_mov_b32_e32 v2, v127
	v_mov_b32_e32 v1, v127
	v_mov_b32_e32 v0, v127
	v_readlane_b32 s53, v255, 11
	v_readlane_b32 s54, v255, 12
	v_readlane_b32 s55, v255, 13
	v_readlane_b32 s56, v255, 14
	v_readlane_b32 s57, v255, 15
	v_readlane_b32 s58, v255, 16
	v_readlane_b32 s59, v255, 17
	v_readlane_b32 s62, v255, 20
	v_readlane_b32 s63, v255, 21
	v_readlane_b32 s64, v255, 22
	v_readlane_b32 s65, v255, 23
	v_readlane_b32 s66, v255, 24
	v_readlane_b32 s67, v255, 25
	s_barrier
	s_cbranch_scc1 .LBB0_524
	v_readlane_b32 s52, v254, 54
	s_add_i32 s46, s38, -2
	v_readlane_b32 s60, v254, 62
	v_readlane_b32 s61, v254, 63
	s_add_u32 s41, s60, s42
	s_addc_u32 s44, s61, s43
	s_ashr_i32 s49, s48, 31
	s_lshl_b64 s[42:43], s[48:49], 11
	s_add_u32 s42, s41, s42
	s_addc_u32 s43, s44, s43
	s_ashr_i32 s41, s40, 31
	s_lshl_b64 s[44:45], s[40:41], 11
	s_add_u32 s44, s8, s44
	v_mov_b32_e32 v0, 0
	s_addc_u32 s45, s39, s45
	s_mov_b32 s41, 0
	v_readlane_b32 s53, v254, 55
	v_readlane_b32 s54, v254, 56
	v_readlane_b32 s55, v254, 57
	v_readlane_b32 s56, v254, 58
	v_readlane_b32 s57, v254, 59
	v_readlane_b32 s58, v254, 60
	v_readlane_b32 s59, v254, 61
	v_readlane_b32 s62, v255, 0
	v_readlane_b32 s63, v255, 1
	v_readlane_b32 s64, v255, 2
	v_readlane_b32 s65, v255, 3
	v_readlane_b32 s66, v255, 4
	v_readlane_b32 s67, v255, 5

; #define WAIT_V(n) asm volatile("s_waitcnt vmcnt(" #n ")" ::: "memory")
; #define BAR __builtin_amdgcn_s_barrier()
; template <class Epi>
; __device__ __forceinline__ void gemm_phase(const bfr* __restrict__ A, int lda, const bfr* __restrict__ Bt, int K,
;                                            int nM, int nN, const Epi& epi, bfr* shm, int wv, int nMfull, int ksplit) {
;     ...
;   while (item < nitems) {
;     const bfr* Ak = A + kbeg; const bfr* Bk = Bt + kbeg;
;     f32x4 acc[2][2][4][2];
; #pragma unroll
;     for (int a = 0; a < 2; a++)
; #pragma unroll
;       for (int b = 0; b < 2; b++)
; #pragma unroll
;         for (int m = 0; m < 4; m++)
; #pragma unroll
;           for (int n = 0; n < 2; n++) acc[a][b][m][n] = f32x4{0.f, 0.f, 0.f, 0.f};
;     bf16x8 At[4][2], B0[2][2], B1[2][2];
;     if (wr == 1) BAR;
;     WAIT_V(10); BAR;
;     WAIT_V(6); BAR;
;     for (int t = 0; t < nt - 2; t += 2) {
.LBB0_671:
	s_waitcnt vmcnt(10)
	s_barrier
	s_waitcnt vmcnt(6)
	v_mov_b32_e32 v127, 0
	s_cmp_lt_u32 s22, 3
	v_mov_b32_e32 v126, v127
	v_mov_b32_e32 v125, v127
	v_mov_b32_e32 v124, v127
	v_mov_b32_e32 v123, v127
	v_mov_b32_e32 v122, v127
	v_mov_b32_e32 v121, v127
	v_mov_b32_e32 v120, v127
	v_mov_b32_e32 v119, v127
	v_mov_b32_e32 v118, v127
	v_mov_b32_e32 v117, v127
	v_mov_b32_e32 v116, v127
	v_mov_b32_e32 v115, v127
	v_mov_b32_e32 v114, v127
	v_mov_b32_e32 v113, v127
	v_mov_b32_e32 v112, v127
	v_mov_b32_e32 v111, v127
	v_mov_b32_e32 v110, v127
	v_mov_b32_e32 v109, v127
	v_mov_b32_e32 v108, v127
	v_mov_b32_e32 v107, v127
	v_mov_b32_e32 v106, v127
	v_mov_b32_e32 v105, v127
	v_mov_b32_e32 v104, v127
	v_mov_b32_e32 v103, v127
	v_mov_b32_e32 v102, v127
	v_mov_b32_e32 v101, v127
	v_mov_b32_e32 v100, v127
	v_mov_b32_e32 v99, v127
	v_mov_b32_e32 v98, v127
	v_mov_b32_e32 v97, v127
	v_mov_b32_e32 v96, v127
	v_mov_b32_e32 v95, v127
	v_mov_b32_e32 v94, v127
	v_mov_b32_e32 v93, v127
	v_mov_b32_e32 v92, v127
	v_mov_b32_e32 v91, v127
	v_mov_b32_e32 v90, v127
	v_mov_b32_e32 v89, v127
	v_mov_b32_e32 v88, v127
	v_mov_b32_e32 v87, v127
	v_mov_b32_e32 v86, v127
	v_mov_b32_e32 v85, v127
	v_mov_b32_e32 v84, v127
	v_mov_b32_e32 v83, v127
	v_mov_b32_e32 v82, v127
	v_mov_b32_e32 v81, v127
	v_mov_b32_e32 v80, v127
	v_mov_b32_e32 v79, v127
	v_mov_b32_e32 v78, v127
	v_mov_b32_e32 v77, v127
	v_mov_b32_e32 v76, v127
	v_mov_b32_e32 v75, v127
	v_mov_b32_e32 v74, v127
	v_mov_b32_e32 v73, v127
	v_mov_b32_e32 v72, v127
	v_mov_b32_e32 v71, v127
	v_mov_b32_e32 v70, v127
	v_mov_b32_e32 v69, v127
	v_mov_b32_e32 v68, v127
	v_mov_b32_e32 v67, v127
	v_mov_b32_e32 v66, v127
	v_mov_b32_e32 v65, v127
	v_mov_b32_e32 v64, v127
	v_mov_b32_e32 v63, v127
	v_mov_b32_e32 v62, v127
	v_mov_b32_e32 v61, v127
	v_mov_b32_e32 v60, v127
	v_mov_b32_e32 v59, v127
	v_mov_b32_e32 v58, v127
	v_mov_b32_e32 v57, v127
	v_mov_b32_e32 v56, v127
	v_mov_b32_e32 v55, v127
	v_mov_b32_e32 v54, v127
	v_mov_b32_e32 v53, v127
	v_mov_b32_e32 v52, v127
	v_mov_b32_e32 v51, v127
	v_mov_b32_e32 v50, v127
	v_mov_b32_e32 v49, v127
	v_mov_b32_e32 v48, v127
	v_mov_b32_e32 v47, v127
	v_mov_b32_e32 v46, v127
	v_mov_b32_e32 v45, v127
	v_mov_b32_e32 v44, v127
	v_mov_b32_e32 v43, v127
	v_mov_b32_e32 v42, v127
	v_mov_b32_e32 v41, v127
	v_mov_b32_e32 v40, v127
	v_mov_b32_e32 v39, v127
	v_mov_b32_e32 v38, v127
	v_mov_b32_e32 v37, v127
	v_mov_b32_e32 v36, v127
	v_mov_b32_e32 v35, v127
	v_mov_b32_e32 v34, v127
	v_mov_b32_e32 v33, v127
	v_mov_b32_e32 v32, v127
	v_mov_b32_e32 v31, v127
	v_mov_b32_e32 v30, v127
	v_mov_b32_e32 v29, v127
	v_mov_b32_e32 v28, v127
	v_mov_b32_e32 v27, v127
	v_mov_b32_e32 v26, v127
	v_mov_b32_e32 v25, v127
	v_mov_b32_e32 v24, v127
	v_mov_b32_e32 v23, v127
	v_mov_b32_e32 v22, v127
	v_mov_b32_e32 v21, v127
	v_mov_b32_e32 v20, v127
	v_mov_b32_e32 v19, v127
	v_mov_b32_e32 v18, v127
	v_mov_b32_e32 v17, v127
	v_mov_b32_e32 v16, v127
	v_mov_b32_e32 v15, v127
	v_mov_b32_e32 v14, v127
	v_mov_b32_e32 v13, v127
	v_mov_b32_e32 v12, v127
	v_mov_b32_e32 v11, v127
	v_mov_b32_e32 v10, v127
	v_mov_b32_e32 v9, v127
	v_mov_b32_e32 v8, v127
	v_mov_b32_e32 v7, v127
	v_mov_b32_e32 v6, v127
	v_mov_b32_e32 v5, v127
	v_mov_b32_e32 v4, v127
	v_mov_b32_e32 v3, v127
	v_mov_b32_e32 v2, v127
	v_mov_b32_e32 v1, v127
	v_mov_b32_e32 v0, v127
	s_barrier
	s_cbranch_scc1 .LBB0_674
	s_ashr_i32 s31, s30, 31
	s_ashr_i32 s35, s34, 31
	v_readlane_b32 s60, v254, 54
	s_add_i32 s2, s22, -2
	s_lshl_b64 s[6:7], s[30:31], 11
	s_lshl_b64 s[24:25], s[34:35], 11
	v_readlane_b32 s62, v254, 56
	v_readlane_b32 s63, v254, 57
	s_add_u32 s6, s62, s6
	s_addc_u32 s7, s63, s7
	s_add_u32 s24, s80, s24
	v_mov_b32_e32 v0, 0
	s_addc_u32 s25, s81, s25
	s_mov_b32 s3, 0
	v_readlane_b32 s61, v254, 55
	v_readlane_b32 s64, v254, 58
	v_readlane_b32 s65, v254, 59
	v_readlane_b32 s66, v254, 60
	v_readlane_b32 s67, v254, 61
	v_readlane_b32 s68, v254, 62
	v_readlane_b32 s69, v254, 63
	v_readlane_b32 s70, v255, 0
	v_readlane_b32 s71, v255, 1
	v_readlane_b32 s72, v255, 2
	v_readlane_b32 s73, v255, 3
	v_readlane_b32 s74, v255, 4
	v_readlane_b32 s75, v255, 5

; #define WAIT_V(n) asm volatile("s_waitcnt vmcnt(" #n ")" ::: "memory")
; #define BAR __builtin_amdgcn_s_barrier()
; template <class Epi>
; __device__ __forceinline__ void gemm_phase(const bfr* __restrict__ A, int lda, const bfr* __restrict__ Bt, int K,
;                                            int nM, int nN, const Epi& epi, bfr* shm, int wv, int nMfull, int ksplit) {
;     ...
;   while (item < nitems) {
;     const bfr* Ak = A + kbeg; const bfr* Bk = Bt + kbeg;
;     f32x4 acc[2][2][4][2];
; #pragma unroll
;     for (int a = 0; a < 2; a++)
; #pragma unroll
;       for (int b = 0; b < 2; b++)
; #pragma unroll
;         for (int m = 0; m < 4; m++)
; #pragma unroll
;           for (int n = 0; n < 2; n++) acc[a][b][m][n] = f32x4{0.f, 0.f, 0.f, 0.f};
;     bf16x8 At[4][2], B0[2][2], B1[2][2];
;     if (wr == 1) BAR;
;     WAIT_V(10); BAR;
;     WAIT_V(6); BAR;
;     for (int t = 0; t < nt - 2; t += 2) {
.LBB0_727:
	v_readlane_b32 s60, v255, 10
	s_lshl_b64 s[38:39], s[10:11], 1
	v_readlane_b32 s66, v255, 16
	v_readlane_b32 s67, v255, 17
	s_add_u32 s10, s66, s38
	s_waitcnt vmcnt(10)
	s_barrier
	s_waitcnt vmcnt(6)
	s_addc_u32 s31, s67, s39
	v_mov_b32_e32 v127, 0
	s_cmp_lt_u32 s30, 3
	v_mov_b32_e32 v126, v127
	v_mov_b32_e32 v125, v127
	v_mov_b32_e32 v124, v127
	v_mov_b32_e32 v123, v127
	v_mov_b32_e32 v122, v127
	v_mov_b32_e32 v121, v127
	v_mov_b32_e32 v120, v127
	v_mov_b32_e32 v119, v127
	v_mov_b32_e32 v118, v127
	v_mov_b32_e32 v117, v127
	v_mov_b32_e32 v116, v127
	v_mov_b32_e32 v115, v127
	v_mov_b32_e32 v114, v127
	v_mov_b32_e32 v113, v127
	v_mov_b32_e32 v112, v127
	v_mov_b32_e32 v111, v127
	v_mov_b32_e32 v110, v127
	v_mov_b32_e32 v109, v127
	v_mov_b32_e32 v108, v127
	v_mov_b32_e32 v107, v127
	v_mov_b32_e32 v106, v127
	v_mov_b32_e32 v105, v127
	v_mov_b32_e32 v104, v127
	v_mov_b32_e32 v103, v127
	v_mov_b32_e32 v102, v127
	v_mov_b32_e32 v101, v127
	v_mov_b32_e32 v100, v127
	v_mov_b32_e32 v99, v127
	v_mov_b32_e32 v98, v127
	v_mov_b32_e32 v97, v127
	v_mov_b32_e32 v96, v127
	v_mov_b32_e32 v95, v127
	v_mov_b32_e32 v94, v127
	v_mov_b32_e32 v93, v127
	v_mov_b32_e32 v92, v127
	v_mov_b32_e32 v91, v127
	v_mov_b32_e32 v90, v127
	v_mov_b32_e32 v89, v127
	v_mov_b32_e32 v88, v127
	v_mov_b32_e32 v87, v127
	v_mov_b32_e32 v86, v127
	v_mov_b32_e32 v85, v127
	v_mov_b32_e32 v84, v127
	v_mov_b32_e32 v83, v127
	v_mov_b32_e32 v82, v127
	v_mov_b32_e32 v81, v127
	v_mov_b32_e32 v80, v127
	v_mov_b32_e32 v79, v127
	v_mov_b32_e32 v78, v127
	v_mov_b32_e32 v77, v127
	v_mov_b32_e32 v76, v127
	v_mov_b32_e32 v75, v127
	v_mov_b32_e32 v74, v127
	v_mov_b32_e32 v73, v127
	v_mov_b32_e32 v72, v127
	v_mov_b32_e32 v71, v127
	v_mov_b32_e32 v70, v127
	v_mov_b32_e32 v69, v127
	v_mov_b32_e32 v68, v127
	v_mov_b32_e32 v67, v127
	v_mov_b32_e32 v66, v127
	v_mov_b32_e32 v65, v127
	v_mov_b32_e32 v64, v127
	v_mov_b32_e32 v63, v127
	v_mov_b32_e32 v62, v127
	v_mov_b32_e32 v61, v127
	v_mov_b32_e32 v60, v127
	v_mov_b32_e32 v59, v127
	v_mov_b32_e32 v58, v127
	v_mov_b32_e32 v57, v127
	v_mov_b32_e32 v56, v127
	v_mov_b32_e32 v55, v127
	v_mov_b32_e32 v54, v127
	v_mov_b32_e32 v53, v127
	v_mov_b32_e32 v52, v127
	v_mov_b32_e32 v51, v127
	v_mov_b32_e32 v50, v127
	v_mov_b32_e32 v49, v127
	v_mov_b32_e32 v48, v127
	v_mov_b32_e32 v47, v127
	v_mov_b32_e32 v46, v127
	v_mov_b32_e32 v45, v127
	v_mov_b32_e32 v44, v127
	v_mov_b32_e32 v43, v127
	v_mov_b32_e32 v42, v127
	v_mov_b32_e32 v41, v127
	v_mov_b32_e32 v40, v127
	v_mov_b32_e32 v39, v127
	v_mov_b32_e32 v38, v127
	v_mov_b32_e32 v37, v127
	v_mov_b32_e32 v36, v127
	v_mov_b32_e32 v35, v127
	v_mov_b32_e32 v34, v127
	v_mov_b32_e32 v33, v127
	v_mov_b32_e32 v32, v127
	v_mov_b32_e32 v31, v127
	v_mov_b32_e32 v30, v127
	v_mov_b32_e32 v29, v127
	v_mov_b32_e32 v28, v127
	v_mov_b32_e32 v27, v127
	v_mov_b32_e32 v26, v127
	v_mov_b32_e32 v25, v127
	v_mov_b32_e32 v24, v127
	v_mov_b32_e32 v23, v127
	v_mov_b32_e32 v22, v127
	v_mov_b32_e32 v21, v127
	v_mov_b32_e32 v20, v127
	v_mov_b32_e32 v19, v127
	v_mov_b32_e32 v18, v127
	v_mov_b32_e32 v17, v127
	v_mov_b32_e32 v16, v127
	v_mov_b32_e32 v15, v127
	v_mov_b32_e32 v14, v127
	v_mov_b32_e32 v13, v127
	v_mov_b32_e32 v12, v127
	v_mov_b32_e32 v11, v127
	v_mov_b32_e32 v10, v127
	v_mov_b32_e32 v9, v127
	v_mov_b32_e32 v8, v127
	v_mov_b32_e32 v7, v127
	v_mov_b32_e32 v6, v127
	v_mov_b32_e32 v5, v127
	v_mov_b32_e32 v4, v127
	v_mov_b32_e32 v3, v127
	v_mov_b32_e32 v2, v127
	v_mov_b32_e32 v1, v127
	v_mov_b32_e32 v0, v127
	v_readlane_b32 s61, v255, 11
	v_readlane_b32 s62, v255, 12
	v_readlane_b32 s63, v255, 13
	v_readlane_b32 s64, v255, 14
	v_readlane_b32 s65, v255, 15
	v_readlane_b32 s68, v255, 18
	v_readlane_b32 s69, v255, 19
	v_readlane_b32 s70, v255, 20
	v_readlane_b32 s71, v255, 21
	v_readlane_b32 s72, v255, 22
	v_readlane_b32 s73, v255, 23
	v_readlane_b32 s74, v255, 24
	v_readlane_b32 s75, v255, 25
	s_barrier
	s_cbranch_scc1 .LBB0_730
	s_mul_i32 s40, s36, 0xb00
	s_add_i32 s2, s30, -2
	s_ashr_i32 s41, s40, 31
	s_mul_i32 s34, s95, 0x1600
	s_mul_hi_i32 s35, s95, 0x1600
	s_add_u32 s34, s10, s34
	s_addc_u32 s35, s31, s35
	s_lshl_b64 s[40:41], s[40:41], 1
	s_add_u32 s37, s40, s38
	v_readlane_b32 s60, v254, 54
	s_addc_u32 s39, s41, s39
	v_readlane_b32 s64, v254, 58
	v_readlane_b32 s65, v254, 59
	s_add_u32 s38, s64, s37
	v_mov_b32_e32 v0, 0
	s_addc_u32 s39, s65, s39
	s_mov_b32 s37, 0
	v_readlane_b32 s61, v254, 55
	v_readlane_b32 s62, v254, 56
	v_readlane_b32 s63, v254, 57
	v_readlane_b32 s66, v254, 60
	v_readlane_b32 s67, v254, 61
	v_readlane_b32 s68, v254, 62
	v_readlane_b32 s69, v254, 63
	v_readlane_b32 s70, v255, 0
	v_readlane_b32 s71, v255, 1
	v_readlane_b32 s72, v255, 2
	v_readlane_b32 s73, v255, 3
	v_readlane_b32 s74, v255, 4
	v_readlane_b32 s75, v255, 5

; #define WAIT_V(n) asm volatile("s_waitcnt vmcnt(" #n ")" ::: "memory")
; #define BAR __builtin_amdgcn_s_barrier()
; template <class Epi>
; __device__ __forceinline__ void gemm_phase(const bfr* __restrict__ A, int lda, const bfr* __restrict__ Bt, int K,
;                                            int nM, int nN, const Epi& epi, bfr* shm, int wv, int nMfull, int ksplit) {
;     ...
;   while (item < nitems) {
;     const bfr* Ak = A + kbeg; const bfr* Bk = Bt + kbeg;
;     f32x4 acc[2][2][4][2];
; #pragma unroll
;     for (int a = 0; a < 2; a++)
; #pragma unroll
;       for (int b = 0; b < 2; b++)
; #pragma unroll
;         for (int m = 0; m < 4; m++)
; #pragma unroll
;           for (int n = 0; n < 2; n++) acc[a][b][m][n] = f32x4{0.f, 0.f, 0.f, 0.f};
;     bf16x8 At[4][2], B0[2][2], B1[2][2];
;     if (wr == 1) BAR;
;     WAIT_V(10); BAR;
;     WAIT_V(6); BAR;
;     for (int t = 0; t < nt - 2; t += 2) {
.LBB0_877:
	s_waitcnt vmcnt(10)
	s_barrier
	s_waitcnt vmcnt(6)
	v_mov_b32_e32 v127, 0
	s_cmp_lt_u32 s20, 3
	v_mov_b32_e32 v126, v127
	v_mov_b32_e32 v125, v127
	v_mov_b32_e32 v124, v127
	v_mov_b32_e32 v123, v127
	v_mov_b32_e32 v122, v127
	v_mov_b32_e32 v121, v127
	v_mov_b32_e32 v120, v127
	v_mov_b32_e32 v119, v127
	v_mov_b32_e32 v118, v127
	v_mov_b32_e32 v117, v127
	v_mov_b32_e32 v116, v127
	v_mov_b32_e32 v115, v127
	v_mov_b32_e32 v114, v127
	v_mov_b32_e32 v113, v127
	v_mov_b32_e32 v112, v127
	v_mov_b32_e32 v111, v127
	v_mov_b32_e32 v110, v127
	v_mov_b32_e32 v109, v127
	v_mov_b32_e32 v108, v127
	v_mov_b32_e32 v107, v127
	v_mov_b32_e32 v106, v127
	v_mov_b32_e32 v105, v127
	v_mov_b32_e32 v104, v127
	v_mov_b32_e32 v103, v127
	v_mov_b32_e32 v102, v127
	v_mov_b32_e32 v101, v127
	v_mov_b32_e32 v100, v127
	v_mov_b32_e32 v99, v127
	v_mov_b32_e32 v98, v127
	v_mov_b32_e32 v97, v127
	v_mov_b32_e32 v96, v127
	v_mov_b32_e32 v95, v127
	v_mov_b32_e32 v94, v127
	v_mov_b32_e32 v93, v127
	v_mov_b32_e32 v92, v127
	v_mov_b32_e32 v91, v127
	v_mov_b32_e32 v90, v127
	v_mov_b32_e32 v89, v127
	v_mov_b32_e32 v88, v127
	v_mov_b32_e32 v87, v127
	v_mov_b32_e32 v86, v127
	v_mov_b32_e32 v85, v127
	v_mov_b32_e32 v84, v127
	v_mov_b32_e32 v83, v127
	v_mov_b32_e32 v82, v127
	v_mov_b32_e32 v81, v127
	v_mov_b32_e32 v80, v127
	v_mov_b32_e32 v79, v127
	v_mov_b32_e32 v78, v127
	v_mov_b32_e32 v77, v127
	v_mov_b32_e32 v76, v127
	v_mov_b32_e32 v75, v127
	v_mov_b32_e32 v74, v127
	v_mov_b32_e32 v73, v127
	v_mov_b32_e32 v72, v127
	v_mov_b32_e32 v71, v127
	v_mov_b32_e32 v70, v127
	v_mov_b32_e32 v69, v127
	v_mov_b32_e32 v68, v127
	v_mov_b32_e32 v67, v127
	v_mov_b32_e32 v66, v127
	v_mov_b32_e32 v65, v127
	v_mov_b32_e32 v64, v127
	v_mov_b32_e32 v63, v127
	v_mov_b32_e32 v62, v127
	v_mov_b32_e32 v61, v127
	v_mov_b32_e32 v60, v127
	v_mov_b32_e32 v59, v127
	v_mov_b32_e32 v58, v127
	v_mov_b32_e32 v57, v127
	v_mov_b32_e32 v56, v127
	v_mov_b32_e32 v55, v127
	v_mov_b32_e32 v54, v127
	v_mov_b32_e32 v53, v127
	v_mov_b32_e32 v52, v127
	v_mov_b32_e32 v51, v127
	v_mov_b32_e32 v50, v127
	v_mov_b32_e32 v49, v127
	v_mov_b32_e32 v48, v127
	v_mov_b32_e32 v47, v127
	v_mov_b32_e32 v46, v127
	v_mov_b32_e32 v45, v127
	v_mov_b32_e32 v44, v127
	v_mov_b32_e32 v43, v127
	v_mov_b32_e32 v42, v127
	v_mov_b32_e32 v41, v127
	v_mov_b32_e32 v40, v127
	v_mov_b32_e32 v39, v127
	v_mov_b32_e32 v38, v127
	v_mov_b32_e32 v37, v127
	v_mov_b32_e32 v36, v127
	v_mov_b32_e32 v35, v127
	v_mov_b32_e32 v34, v127
	v_mov_b32_e32 v33, v127
	v_mov_b32_e32 v32, v127
	v_mov_b32_e32 v31, v127
	v_mov_b32_e32 v30, v127
	v_mov_b32_e32 v29, v127
	v_mov_b32_e32 v28, v127
	v_mov_b32_e32 v27, v127
	v_mov_b32_e32 v26, v127
	v_mov_b32_e32 v25, v127
	v_mov_b32_e32 v24, v127
	v_mov_b32_e32 v23, v127
	v_mov_b32_e32 v22, v127
	v_mov_b32_e32 v21, v127
	v_mov_b32_e32 v20, v127
	v_mov_b32_e32 v19, v127
	v_mov_b32_e32 v18, v127
	v_mov_b32_e32 v17, v127
	v_mov_b32_e32 v16, v127
	v_mov_b32_e32 v15, v127
	v_mov_b32_e32 v14, v127
	v_mov_b32_e32 v13, v127
	v_mov_b32_e32 v12, v127
	v_mov_b32_e32 v11, v127
	v_mov_b32_e32 v10, v127
	v_mov_b32_e32 v9, v127
	v_mov_b32_e32 v8, v127
	v_mov_b32_e32 v7, v127
	v_mov_b32_e32 v6, v127
	v_mov_b32_e32 v5, v127
	v_mov_b32_e32 v4, v127
	v_mov_b32_e32 v3, v127
	v_mov_b32_e32 v2, v127
	v_mov_b32_e32 v1, v127
	v_mov_b32_e32 v0, v127
	s_barrier
	s_cbranch_scc1 .LBB0_880
	s_ashr_i32 s29, s28, 31
	s_ashr_i32 s31, s30, 31
	v_readlane_b32 s56, v254, 54
	s_add_i32 s21, s20, -2
	s_lshl_b64 s[4:5], s[28:29], 11
	s_lshl_b64 s[22:23], s[30:31], 11
	v_readlane_b32 s58, v254, 56
	v_readlane_b32 s59, v254, 57
	s_add_u32 s4, s58, s4
	s_addc_u32 s5, s59, s5
	s_add_u32 s22, s80, s22
	v_mov_b32_e32 v0, 0
	s_addc_u32 s23, s81, s23
	s_mov_b32 s24, 0
	v_readlane_b32 s57, v254, 55
	v_readlane_b32 s60, v254, 58
	v_readlane_b32 s61, v254, 59
	v_readlane_b32 s62, v254, 60
	v_readlane_b32 s63, v254, 61
	v_readlane_b32 s64, v254, 62
	v_readlane_b32 s65, v254, 63
	v_readlane_b32 s66, v255, 0
	v_readlane_b32 s67, v255, 1
	v_readlane_b32 s68, v255, 2
	v_readlane_b32 s69, v255, 3
	v_readlane_b32 s70, v255, 4
	v_readlane_b32 s71, v255, 5

; #define WAIT_V(n) asm volatile("s_waitcnt vmcnt(" #n ")" ::: "memory")
; #define BAR __builtin_amdgcn_s_barrier()
; template <class Epi>
; __device__ __forceinline__ void gemm_phase(const bfr* __restrict__ A, int lda, const bfr* __restrict__ Bt, int K,
;                                            int nM, int nN, const Epi& epi, bfr* shm, int wv, int nMfull, int ksplit) {
;     ...
;   while (item < nitems) {
;     const bfr* Ak = A + kbeg; const bfr* Bk = Bt + kbeg;
;     f32x4 acc[2][2][4][2];
; #pragma unroll
;     for (int a = 0; a < 2; a++)
; #pragma unroll
;       for (int b = 0; b < 2; b++)
; #pragma unroll
;         for (int m = 0; m < 4; m++)
; #pragma unroll
;           for (int n = 0; n < 2; n++) acc[a][b][m][n] = f32x4{0.f, 0.f, 0.f, 0.f};
;     bf16x8 At[4][2], B0[2][2], B1[2][2];
;     if (wr == 1) BAR;
;     WAIT_V(10); BAR;
;     WAIT_V(6); BAR;
;     for (int t = 0; t < nt - 2; t += 2) {
.LBB0_933:
	v_readlane_b32 s60, v255, 10
	s_lshl_b64 s[36:37], s[8:9], 1
	v_readlane_b32 s66, v255, 16
	v_readlane_b32 s67, v255, 17
	s_add_u32 s8, s66, s36
	s_waitcnt vmcnt(10)
	s_barrier
	s_waitcnt vmcnt(6)
	s_addc_u32 s29, s67, s37
	v_mov_b32_e32 v127, 0
	s_cmp_lt_u32 s28, 3
	v_mov_b32_e32 v126, v127
	v_mov_b32_e32 v125, v127
	v_mov_b32_e32 v124, v127
	v_mov_b32_e32 v123, v127
	v_mov_b32_e32 v122, v127
	v_mov_b32_e32 v121, v127
	v_mov_b32_e32 v120, v127
	v_mov_b32_e32 v119, v127
	v_mov_b32_e32 v118, v127
	v_mov_b32_e32 v117, v127
	v_mov_b32_e32 v116, v127
	v_mov_b32_e32 v115, v127
	v_mov_b32_e32 v114, v127
	v_mov_b32_e32 v113, v127
	v_mov_b32_e32 v112, v127
	v_mov_b32_e32 v111, v127
	v_mov_b32_e32 v110, v127
	v_mov_b32_e32 v109, v127
	v_mov_b32_e32 v108, v127
	v_mov_b32_e32 v107, v127
	v_mov_b32_e32 v106, v127
	v_mov_b32_e32 v105, v127
	v_mov_b32_e32 v104, v127
	v_mov_b32_e32 v103, v127
	v_mov_b32_e32 v102, v127
	v_mov_b32_e32 v101, v127
	v_mov_b32_e32 v100, v127
	v_mov_b32_e32 v99, v127
	v_mov_b32_e32 v98, v127
	v_mov_b32_e32 v97, v127
	v_mov_b32_e32 v96, v127
	v_mov_b32_e32 v95, v127
	v_mov_b32_e32 v94, v127
	v_mov_b32_e32 v93, v127
	v_mov_b32_e32 v92, v127
	v_mov_b32_e32 v91, v127
	v_mov_b32_e32 v90, v127
	v_mov_b32_e32 v89, v127
	v_mov_b32_e32 v88, v127
	v_mov_b32_e32 v87, v127
	v_mov_b32_e32 v86, v127
	v_mov_b32_e32 v85, v127
	v_mov_b32_e32 v84, v127
	v_mov_b32_e32 v83, v127
	v_mov_b32_e32 v82, v127
	v_mov_b32_e32 v81, v127
	v_mov_b32_e32 v80, v127
	v_mov_b32_e32 v79, v127
	v_mov_b32_e32 v78, v127
	v_mov_b32_e32 v77, v127
	v_mov_b32_e32 v76, v127
	v_mov_b32_e32 v75, v127
	v_mov_b32_e32 v74, v127
	v_mov_b32_e32 v73, v127
	v_mov_b32_e32 v72, v127
	v_mov_b32_e32 v71, v127
	v_mov_b32_e32 v70, v127
	v_mov_b32_e32 v69, v127
	v_mov_b32_e32 v68, v127
	v_mov_b32_e32 v67, v127
	v_mov_b32_e32 v66, v127
	v_mov_b32_e32 v65, v127
	v_mov_b32_e32 v64, v127
	v_mov_b32_e32 v63, v127
	v_mov_b32_e32 v62, v127
	v_mov_b32_e32 v61, v127
	v_mov_b32_e32 v60, v127
	v_mov_b32_e32 v59, v127
	v_mov_b32_e32 v58, v127
	v_mov_b32_e32 v57, v127
	v_mov_b32_e32 v56, v127
	v_mov_b32_e32 v55, v127
	v_mov_b32_e32 v54, v127
	v_mov_b32_e32 v53, v127
	v_mov_b32_e32 v52, v127
	v_mov_b32_e32 v51, v127
	v_mov_b32_e32 v50, v127
	v_mov_b32_e32 v49, v127
	v_mov_b32_e32 v48, v127
	v_mov_b32_e32 v47, v127
	v_mov_b32_e32 v46, v127
	v_mov_b32_e32 v45, v127
	v_mov_b32_e32 v44, v127
	v_mov_b32_e32 v43, v127
	v_mov_b32_e32 v42, v127
	v_mov_b32_e32 v41, v127
	v_mov_b32_e32 v40, v127
	v_mov_b32_e32 v39, v127
	v_mov_b32_e32 v38, v127
	v_mov_b32_e32 v37, v127
	v_mov_b32_e32 v36, v127
	v_mov_b32_e32 v35, v127
	v_mov_b32_e32 v34, v127
	v_mov_b32_e32 v33, v127
	v_mov_b32_e32 v32, v127
	v_mov_b32_e32 v31, v127
	v_mov_b32_e32 v30, v127
	v_mov_b32_e32 v29, v127
	v_mov_b32_e32 v28, v127
	v_mov_b32_e32 v27, v127
	v_mov_b32_e32 v26, v127
	v_mov_b32_e32 v25, v127
	v_mov_b32_e32 v24, v127
	v_mov_b32_e32 v23, v127
	v_mov_b32_e32 v22, v127
	v_mov_b32_e32 v21, v127
	v_mov_b32_e32 v20, v127
	v_mov_b32_e32 v19, v127
	v_mov_b32_e32 v18, v127
	v_mov_b32_e32 v17, v127
	v_mov_b32_e32 v16, v127
	v_mov_b32_e32 v15, v127
	v_mov_b32_e32 v14, v127
	v_mov_b32_e32 v13, v127
	v_mov_b32_e32 v12, v127
	v_mov_b32_e32 v11, v127
	v_mov_b32_e32 v10, v127
	v_mov_b32_e32 v9, v127
	v_mov_b32_e32 v8, v127
	v_mov_b32_e32 v7, v127
	v_mov_b32_e32 v6, v127
	v_mov_b32_e32 v5, v127
	v_mov_b32_e32 v4, v127
	v_mov_b32_e32 v3, v127
	v_mov_b32_e32 v2, v127
	v_mov_b32_e32 v1, v127
	v_mov_b32_e32 v0, v127
	v_readlane_b32 s61, v255, 11
	v_readlane_b32 s62, v255, 12
	v_readlane_b32 s63, v255, 13
	v_readlane_b32 s64, v255, 14
	v_readlane_b32 s65, v255, 15
	v_readlane_b32 s68, v255, 18
	v_readlane_b32 s69, v255, 19
	v_readlane_b32 s70, v255, 20
	v_readlane_b32 s71, v255, 21
	v_readlane_b32 s72, v255, 22
	v_readlane_b32 s73, v255, 23
	v_readlane_b32 s74, v255, 24
	v_readlane_b32 s75, v255, 25
	s_barrier
	s_cbranch_scc1 .LBB0_936
	s_mul_i32 s40, s34, 0xb00
	s_add_i32 s35, s28, -2
	s_ashr_i32 s41, s40, 31
	s_mul_i32 s30, s93, 0x1600
	s_mul_hi_i32 s31, s93, 0x1600
	s_add_u32 s30, s8, s30
	s_addc_u32 s31, s29, s31
	s_lshl_b64 s[40:41], s[40:41], 1
	s_add_u32 s36, s40, s36
	v_readlane_b32 s60, v254, 54
	s_addc_u32 s37, s41, s37
	v_readlane_b32 s64, v254, 58
	v_readlane_b32 s65, v254, 59
	s_add_u32 s36, s64, s36
	v_mov_b32_e32 v0, 0
	s_addc_u32 s37, s65, s37
	s_mov_b32 s39, 0
	v_readlane_b32 s61, v254, 55
	v_readlane_b32 s62, v254, 56
	v_readlane_b32 s63, v254, 57
	v_readlane_b32 s66, v254, 60
	v_readlane_b32 s67, v254, 61
	v_readlane_b32 s68, v254, 62
	v_readlane_b32 s69, v254, 63
	v_readlane_b32 s70, v255, 0
	v_readlane_b32 s71, v255, 1
	v_readlane_b32 s72, v255, 2
	v_readlane_b32 s73, v255, 3
	v_readlane_b32 s74, v255, 4
	v_readlane_b32 s75, v255, 5

; #define WAIT_V(n) asm volatile("s_waitcnt vmcnt(" #n ")" ::: "memory")
; #define BAR __builtin_amdgcn_s_barrier()
; template <class Epi>
; __device__ __forceinline__ void gemm_phase(const bfr* __restrict__ A, int lda, const bfr* __restrict__ Bt, int K,
;                                            int nM, int nN, const Epi& epi, bfr* shm, int wv, int nMfull, int ksplit) {
;     ...
;   while (item < nitems) {
;     const bfr* Ak = A + kbeg; const bfr* Bk = Bt + kbeg;
;     f32x4 acc[2][2][4][2];
; #pragma unroll
;     for (int a = 0; a < 2; a++)
; #pragma unroll
;       for (int b = 0; b < 2; b++)
; #pragma unroll
;         for (int m = 0; m < 4; m++)
; #pragma unroll
;           for (int n = 0; n < 2; n++) acc[a][b][m][n] = f32x4{0.f, 0.f, 0.f, 0.f};
;     bf16x8 At[4][2], B0[2][2], B1[2][2];
;     if (wr == 1) BAR;
;     WAIT_V(10); BAR;
;     WAIT_V(6); BAR;
;     for (int t = 0; t < nt - 2; t += 2) {
.LBB0_1084:
	s_waitcnt vmcnt(10)
	s_barrier
	s_waitcnt vmcnt(6)
	v_mov_b32_e32 v127, 0
	s_cmp_lt_u32 s38, 3
	v_mov_b32_e32 v126, v127
	v_mov_b32_e32 v125, v127
	v_mov_b32_e32 v124, v127
	v_mov_b32_e32 v123, v127
	v_mov_b32_e32 v122, v127
	v_mov_b32_e32 v121, v127
	v_mov_b32_e32 v120, v127
	v_mov_b32_e32 v119, v127
	v_mov_b32_e32 v118, v127
	v_mov_b32_e32 v117, v127
	v_mov_b32_e32 v116, v127
	v_mov_b32_e32 v115, v127
	v_mov_b32_e32 v114, v127
	v_mov_b32_e32 v113, v127
	v_mov_b32_e32 v112, v127
	v_mov_b32_e32 v111, v127
	v_mov_b32_e32 v110, v127
	v_mov_b32_e32 v109, v127
	v_mov_b32_e32 v108, v127
	v_mov_b32_e32 v107, v127
	v_mov_b32_e32 v106, v127
	v_mov_b32_e32 v105, v127
	v_mov_b32_e32 v104, v127
	v_mov_b32_e32 v103, v127
	v_mov_b32_e32 v102, v127
	v_mov_b32_e32 v101, v127
	v_mov_b32_e32 v100, v127
	v_mov_b32_e32 v99, v127
	v_mov_b32_e32 v98, v127
	v_mov_b32_e32 v97, v127
	v_mov_b32_e32 v96, v127
	v_mov_b32_e32 v95, v127
	v_mov_b32_e32 v94, v127
	v_mov_b32_e32 v93, v127
	v_mov_b32_e32 v92, v127
	v_mov_b32_e32 v91, v127
	v_mov_b32_e32 v90, v127
	v_mov_b32_e32 v89, v127
	v_mov_b32_e32 v88, v127
	v_mov_b32_e32 v87, v127
	v_mov_b32_e32 v86, v127
	v_mov_b32_e32 v85, v127
	v_mov_b32_e32 v84, v127
	v_mov_b32_e32 v83, v127
	v_mov_b32_e32 v82, v127
	v_mov_b32_e32 v81, v127
	v_mov_b32_e32 v80, v127
	v_mov_b32_e32 v79, v127
	v_mov_b32_e32 v78, v127
	v_mov_b32_e32 v77, v127
	v_mov_b32_e32 v76, v127
	v_mov_b32_e32 v75, v127
	v_mov_b32_e32 v74, v127
	v_mov_b32_e32 v73, v127
	v_mov_b32_e32 v72, v127
	v_mov_b32_e32 v71, v127
	v_mov_b32_e32 v70, v127
	v_mov_b32_e32 v69, v127
	v_mov_b32_e32 v68, v127
	v_mov_b32_e32 v67, v127
	v_mov_b32_e32 v66, v127
	v_mov_b32_e32 v65, v127
	v_mov_b32_e32 v64, v127
	v_mov_b32_e32 v63, v127
	v_mov_b32_e32 v62, v127
	v_mov_b32_e32 v61, v127
	v_mov_b32_e32 v60, v127
	v_mov_b32_e32 v59, v127
	v_mov_b32_e32 v58, v127
	v_mov_b32_e32 v57, v127
	v_mov_b32_e32 v56, v127
	v_mov_b32_e32 v55, v127
	v_mov_b32_e32 v54, v127
	v_mov_b32_e32 v53, v127
	v_mov_b32_e32 v52, v127
	v_mov_b32_e32 v51, v127
	v_mov_b32_e32 v50, v127
	v_mov_b32_e32 v49, v127
	v_mov_b32_e32 v48, v127
	v_mov_b32_e32 v47, v127
	v_mov_b32_e32 v46, v127
	v_mov_b32_e32 v45, v127
	v_mov_b32_e32 v44, v127
	v_mov_b32_e32 v43, v127
	v_mov_b32_e32 v42, v127
	v_mov_b32_e32 v41, v127
	v_mov_b32_e32 v40, v127
	v_mov_b32_e32 v39, v127
	v_mov_b32_e32 v38, v127
	v_mov_b32_e32 v37, v127
	v_mov_b32_e32 v36, v127
	v_mov_b32_e32 v35, v127
	v_mov_b32_e32 v34, v127
	v_mov_b32_e32 v33, v127
	v_mov_b32_e32 v32, v127
	v_mov_b32_e32 v31, v127
	v_mov_b32_e32 v30, v127
	v_mov_b32_e32 v29, v127
	v_mov_b32_e32 v28, v127
	v_mov_b32_e32 v27, v127
	v_mov_b32_e32 v26, v127
	v_mov_b32_e32 v25, v127
	v_mov_b32_e32 v24, v127
	v_mov_b32_e32 v23, v127
	v_mov_b32_e32 v22, v127
	v_mov_b32_e32 v21, v127
	v_mov_b32_e32 v20, v127
	v_mov_b32_e32 v19, v127
	v_mov_b32_e32 v18, v127
	v_mov_b32_e32 v17, v127
	v_mov_b32_e32 v16, v127
	v_mov_b32_e32 v15, v127
	v_mov_b32_e32 v14, v127
	v_mov_b32_e32 v13, v127
	v_mov_b32_e32 v12, v127
	v_mov_b32_e32 v11, v127
	v_mov_b32_e32 v10, v127
	v_mov_b32_e32 v9, v127
	v_mov_b32_e32 v8, v127
	v_mov_b32_e32 v7, v127
	v_mov_b32_e32 v6, v127
	v_mov_b32_e32 v5, v127
	v_mov_b32_e32 v4, v127
	v_mov_b32_e32 v3, v127
	v_mov_b32_e32 v2, v127
	v_mov_b32_e32 v1, v127
	v_mov_b32_e32 v0, v127
	s_barrier
	s_cbranch_scc1 .LBB0_1087
	v_readlane_b32 s52, v254, 54
	s_ashr_i32 s49, s48, 31
	s_ashr_i32 s47, s46, 31
	v_readlane_b32 s62, v255, 0
	v_readlane_b32 s63, v255, 1
	s_add_i32 s39, s38, -2
	s_lshl_b64 s[2:3], s[48:49], 11
	s_lshl_b64 s[36:37], s[46:47], 11
	v_readlane_b32 s53, v254, 55
	v_readlane_b32 s54, v254, 56
	v_readlane_b32 s55, v254, 57
	v_readlane_b32 s56, v254, 58
	v_readlane_b32 s57, v254, 59
	v_readlane_b32 s58, v254, 60
	v_readlane_b32 s59, v254, 61
	v_readlane_b32 s60, v254, 62
	v_readlane_b32 s61, v254, 63
	v_readlane_b32 s64, v255, 2
	v_readlane_b32 s65, v255, 3
	v_readlane_b32 s66, v255, 4
	v_readlane_b32 s67, v255, 5
	s_mov_b64 s[50:51], s[62:63]
	s_add_u32 s2, s50, s2
	v_readlane_b32 s52, v255, 10
	s_addc_u32 s3, s51, s3
	v_readlane_b32 s56, v255, 14
	v_readlane_b32 s57, v255, 15
	s_add_u32 s36, s56, s36
	v_mov_b32_e32 v0, 0
	s_addc_u32 s37, s57, s37
	s_mov_b32 s40, 0
	v_readlane_b32 s53, v255, 11
	v_readlane_b32 s54, v255, 12
	v_readlane_b32 s55, v255, 13
	v_readlane_b32 s58, v255, 16
	v_readlane_b32 s59, v255, 17
	v_readlane_b32 s60, v255, 18
	v_readlane_b32 s61, v255, 19
	v_readlane_b32 s62, v255, 20
	v_readlane_b32 s63, v255, 21
	v_readlane_b32 s64, v255, 22
	v_readlane_b32 s65, v255, 23
	v_readlane_b32 s66, v255, 24
	v_readlane_b32 s67, v255, 25

; #define WAIT_V(n) asm volatile("s_waitcnt vmcnt(" #n ")" ::: "memory")
; #define BAR __builtin_amdgcn_s_barrier()
; template <class Epi>
; __device__ __forceinline__ void gemm_phase(const bfr* __restrict__ A, int lda, const bfr* __restrict__ Bt, int K,
;                                            int nM, int nN, const Epi& epi, bfr* shm, int wv, int nMfull, int ksplit) {
;     ...
;   while (item < nitems) {
;     const bfr* Ak = A + kbeg; const bfr* Bk = Bt + kbeg;
;     f32x4 acc[2][2][4][2];
; #pragma unroll
;     for (int a = 0; a < 2; a++)
; #pragma unroll
;       for (int b = 0; b < 2; b++)
; #pragma unroll
;         for (int m = 0; m < 4; m++)
; #pragma unroll
;           for (int n = 0; n < 2; n++) acc[a][b][m][n] = f32x4{0.f, 0.f, 0.f, 0.f};
;     bf16x8 At[4][2], B0[2][2], B1[2][2];
;     if (wr == 1) BAR;
;     WAIT_V(10); BAR;
;     WAIT_V(6); BAR;
;     for (int t = 0; t < nt - 2; t += 2) {
.LBB0_1214:
	s_waitcnt vmcnt(10)
	s_barrier
	s_waitcnt vmcnt(6)
	v_mov_b32_e32 v127, 0
	s_cmp_lt_u32 s38, 3
	v_mov_b32_e32 v126, v127
	v_mov_b32_e32 v125, v127
	v_mov_b32_e32 v124, v127
	v_mov_b32_e32 v123, v127
	v_mov_b32_e32 v122, v127
	v_mov_b32_e32 v121, v127
	v_mov_b32_e32 v120, v127
	v_mov_b32_e32 v119, v127
	v_mov_b32_e32 v118, v127
	v_mov_b32_e32 v117, v127
	v_mov_b32_e32 v116, v127
	v_mov_b32_e32 v115, v127
	v_mov_b32_e32 v114, v127
	v_mov_b32_e32 v113, v127
	v_mov_b32_e32 v112, v127
	v_mov_b32_e32 v111, v127
	v_mov_b32_e32 v110, v127
	v_mov_b32_e32 v109, v127
	v_mov_b32_e32 v108, v127
	v_mov_b32_e32 v107, v127
	v_mov_b32_e32 v106, v127
	v_mov_b32_e32 v105, v127
	v_mov_b32_e32 v104, v127
	v_mov_b32_e32 v103, v127
	v_mov_b32_e32 v102, v127
	v_mov_b32_e32 v101, v127
	v_mov_b32_e32 v100, v127
	v_mov_b32_e32 v99, v127
	v_mov_b32_e32 v98, v127
	v_mov_b32_e32 v97, v127
	v_mov_b32_e32 v96, v127
	v_mov_b32_e32 v95, v127
	v_mov_b32_e32 v94, v127
	v_mov_b32_e32 v93, v127
	v_mov_b32_e32 v92, v127
	v_mov_b32_e32 v91, v127
	v_mov_b32_e32 v90, v127
	v_mov_b32_e32 v89, v127
	v_mov_b32_e32 v88, v127
	v_mov_b32_e32 v87, v127
	v_mov_b32_e32 v86, v127
	v_mov_b32_e32 v85, v127
	v_mov_b32_e32 v84, v127
	v_mov_b32_e32 v83, v127
	v_mov_b32_e32 v82, v127
	v_mov_b32_e32 v81, v127
	v_mov_b32_e32 v80, v127
	v_mov_b32_e32 v79, v127
	v_mov_b32_e32 v78, v127
	v_mov_b32_e32 v77, v127
	v_mov_b32_e32 v76, v127
	v_mov_b32_e32 v75, v127
	v_mov_b32_e32 v74, v127
	v_mov_b32_e32 v73, v127
	v_mov_b32_e32 v72, v127
	v_mov_b32_e32 v71, v127
	v_mov_b32_e32 v70, v127
	v_mov_b32_e32 v69, v127
	v_mov_b32_e32 v68, v127
	v_mov_b32_e32 v67, v127
	v_mov_b32_e32 v66, v127
	v_mov_b32_e32 v65, v127
	v_mov_b32_e32 v64, v127
	v_mov_b32_e32 v63, v127
	v_mov_b32_e32 v62, v127
	v_mov_b32_e32 v61, v127
	v_mov_b32_e32 v60, v127
	v_mov_b32_e32 v59, v127
	v_mov_b32_e32 v58, v127
	v_mov_b32_e32 v57, v127
	v_mov_b32_e32 v56, v127
	v_mov_b32_e32 v55, v127
	v_mov_b32_e32 v54, v127
	v_mov_b32_e32 v53, v127
	v_mov_b32_e32 v52, v127
	v_mov_b32_e32 v51, v127
	v_mov_b32_e32 v50, v127
	v_mov_b32_e32 v49, v127
	v_mov_b32_e32 v48, v127
	v_mov_b32_e32 v47, v127
	v_mov_b32_e32 v46, v127
	v_mov_b32_e32 v45, v127
	v_mov_b32_e32 v44, v127
	v_mov_b32_e32 v43, v127
	v_mov_b32_e32 v42, v127
	v_mov_b32_e32 v41, v127
	v_mov_b32_e32 v40, v127
	v_mov_b32_e32 v39, v127
	v_mov_b32_e32 v38, v127
	v_mov_b32_e32 v37, v127
	v_mov_b32_e32 v36, v127
	v_mov_b32_e32 v35, v127
	v_mov_b32_e32 v34, v127
	v_mov_b32_e32 v33, v127
	v_mov_b32_e32 v32, v127
	v_mov_b32_e32 v31, v127
	v_mov_b32_e32 v30, v127
	v_mov_b32_e32 v29, v127
	v_mov_b32_e32 v28, v127
	v_mov_b32_e32 v27, v127
	v_mov_b32_e32 v26, v127
	v_mov_b32_e32 v25, v127
	v_mov_b32_e32 v24, v127
	v_mov_b32_e32 v23, v127
	v_mov_b32_e32 v22, v127
	v_mov_b32_e32 v21, v127
	v_mov_b32_e32 v20, v127
	v_mov_b32_e32 v19, v127
	v_mov_b32_e32 v18, v127
	v_mov_b32_e32 v17, v127
	v_mov_b32_e32 v16, v127
	v_mov_b32_e32 v15, v127
	v_mov_b32_e32 v14, v127
	v_mov_b32_e32 v13, v127
	v_mov_b32_e32 v12, v127
	v_mov_b32_e32 v11, v127
	v_mov_b32_e32 v10, v127
	v_mov_b32_e32 v9, v127
	v_mov_b32_e32 v8, v127
	v_mov_b32_e32 v7, v127
	v_mov_b32_e32 v6, v127
	v_mov_b32_e32 v5, v127
	v_mov_b32_e32 v4, v127
	v_mov_b32_e32 v3, v127
	v_mov_b32_e32 v2, v127
	v_mov_b32_e32 v1, v127
	v_mov_b32_e32 v0, v127
	s_barrier
	s_cbranch_scc1 .LBB0_1217
	s_ashr_i32 s49, s48, 31
	s_ashr_i32 s41, s40, 31
	v_readlane_b32 s4, v254, 54
	s_add_i32 s31, s38, -2
	s_lshl_b64 s[42:43], s[48:49], 11
	s_lshl_b64 s[44:45], s[40:41], 11
	v_readlane_b32 s16, v255, 2
	v_readlane_b32 s5, v254, 55
	v_readlane_b32 s6, v254, 56
	v_readlane_b32 s7, v254, 57
	v_readlane_b32 s8, v254, 58
	v_readlane_b32 s9, v254, 59
	v_readlane_b32 s10, v254, 60
	v_readlane_b32 s11, v254, 61
	v_readlane_b32 s12, v254, 62
	v_readlane_b32 s13, v254, 63
	v_readlane_b32 s14, v255, 0
	v_readlane_b32 s15, v255, 1
	v_readlane_b32 s17, v255, 3
	v_readlane_b32 s18, v255, 4
	v_readlane_b32 s19, v255, 5
	s_add_u32 s42, s16, s42
	s_addc_u32 s43, s17, s43
	v_readlane_b32 s4, v255, 10
	v_readlane_b32 s12, v255, 18
	v_readlane_b32 s13, v255, 19
	s_add_u32 s44, s12, s44
	v_mov_b32_e32 v0, 0
	s_addc_u32 s45, s13, s45
	s_mov_b32 s39, 0
	v_readlane_b32 s5, v255, 11
	v_readlane_b32 s6, v255, 12
	v_readlane_b32 s7, v255, 13
	v_readlane_b32 s8, v255, 14
	v_readlane_b32 s9, v255, 15
	v_readlane_b32 s10, v255, 16
	v_readlane_b32 s11, v255, 17
	v_readlane_b32 s14, v255, 20
	v_readlane_b32 s15, v255, 21
	v_readlane_b32 s16, v255, 22
	v_readlane_b32 s17, v255, 23
	v_readlane_b32 s18, v255, 24
	v_readlane_b32 s19, v255, 25

; #define WAIT_V(n) asm volatile("s_waitcnt vmcnt(" #n ")" ::: "memory")
; #define BAR __builtin_amdgcn_s_barrier()
; template <class Epi>
; __device__ __forceinline__ void gemm_phase(const bfr* __restrict__ A, int lda, const bfr* __restrict__ Bt, int K,
;                                            int nM, int nN, const Epi& epi, bfr* shm, int wv, int nMfull, int ksplit) {
;     ...
;   while (item < nitems) {
;     const bfr* Ak = A + kbeg; const bfr* Bk = Bt + kbeg;
;     f32x4 acc[2][2][4][2];
; #pragma unroll
;     for (int a = 0; a < 2; a++)
; #pragma unroll
;       for (int b = 0; b < 2; b++)
; #pragma unroll
;         for (int m = 0; m < 4; m++)
; #pragma unroll
;           for (int n = 0; n < 2; n++) acc[a][b][m][n] = f32x4{0.f, 0.f, 0.f, 0.f};
;     bf16x8 At[4][2], B0[2][2], B1[2][2];
;     if (wr == 1) BAR;
;     WAIT_V(10); BAR;
;     WAIT_V(6); BAR;
;     for (int t = 0; t < nt - 2; t += 2) {
.LBB0_1325:
	s_waitcnt vmcnt(10)
	s_barrier
	s_waitcnt vmcnt(6)
	v_mov_b32_e32 v127, 0
	s_cmp_lt_u32 s48, 3
	v_mov_b32_e32 v126, v127
	v_mov_b32_e32 v125, v127
	v_mov_b32_e32 v124, v127
	v_mov_b32_e32 v123, v127
	v_mov_b32_e32 v122, v127
	v_mov_b32_e32 v121, v127
	v_mov_b32_e32 v120, v127
	v_mov_b32_e32 v119, v127
	v_mov_b32_e32 v118, v127
	v_mov_b32_e32 v117, v127
	v_mov_b32_e32 v116, v127
	v_mov_b32_e32 v115, v127
	v_mov_b32_e32 v114, v127
	v_mov_b32_e32 v113, v127
	v_mov_b32_e32 v112, v127
	v_mov_b32_e32 v111, v127
	v_mov_b32_e32 v110, v127
	v_mov_b32_e32 v109, v127
	v_mov_b32_e32 v108, v127
	v_mov_b32_e32 v107, v127
	v_mov_b32_e32 v106, v127
	v_mov_b32_e32 v105, v127
	v_mov_b32_e32 v104, v127
	v_mov_b32_e32 v103, v127
	v_mov_b32_e32 v102, v127
	v_mov_b32_e32 v101, v127
	v_mov_b32_e32 v100, v127
	v_mov_b32_e32 v99, v127
	v_mov_b32_e32 v98, v127
	v_mov_b32_e32 v97, v127
	v_mov_b32_e32 v96, v127
	v_mov_b32_e32 v95, v127
	v_mov_b32_e32 v94, v127
	v_mov_b32_e32 v93, v127
	v_mov_b32_e32 v92, v127
	v_mov_b32_e32 v91, v127
	v_mov_b32_e32 v90, v127
	v_mov_b32_e32 v89, v127
	v_mov_b32_e32 v88, v127
	v_mov_b32_e32 v87, v127
	v_mov_b32_e32 v86, v127
	v_mov_b32_e32 v85, v127
	v_mov_b32_e32 v84, v127
	v_mov_b32_e32 v83, v127
	v_mov_b32_e32 v82, v127
	v_mov_b32_e32 v81, v127
	v_mov_b32_e32 v80, v127
	v_mov_b32_e32 v79, v127
	v_mov_b32_e32 v78, v127
	v_mov_b32_e32 v77, v127
	v_mov_b32_e32 v76, v127
	v_mov_b32_e32 v75, v127
	v_mov_b32_e32 v74, v127
	v_mov_b32_e32 v73, v127
	v_mov_b32_e32 v72, v127
	v_mov_b32_e32 v71, v127
	v_mov_b32_e32 v70, v127
	v_mov_b32_e32 v69, v127
	v_mov_b32_e32 v68, v127
	v_mov_b32_e32 v67, v127
	v_mov_b32_e32 v66, v127
	v_mov_b32_e32 v65, v127
	v_mov_b32_e32 v64, v127
	v_mov_b32_e32 v63, v127
	v_mov_b32_e32 v62, v127
	v_mov_b32_e32 v61, v127
	v_mov_b32_e32 v60, v127
	v_mov_b32_e32 v59, v127
	v_mov_b32_e32 v58, v127
	v_mov_b32_e32 v57, v127
	v_mov_b32_e32 v56, v127
	v_mov_b32_e32 v55, v127
	v_mov_b32_e32 v54, v127
	v_mov_b32_e32 v53, v127
	v_mov_b32_e32 v52, v127
	v_mov_b32_e32 v51, v127
	v_mov_b32_e32 v50, v127
	v_mov_b32_e32 v49, v127
	v_mov_b32_e32 v48, v127
	v_mov_b32_e32 v47, v127
	v_mov_b32_e32 v46, v127
	v_mov_b32_e32 v45, v127
	v_mov_b32_e32 v44, v127
	v_mov_b32_e32 v43, v127
	v_mov_b32_e32 v42, v127
	v_mov_b32_e32 v41, v127
	v_mov_b32_e32 v40, v127
	v_mov_b32_e32 v39, v127
	v_mov_b32_e32 v38, v127
	v_mov_b32_e32 v37, v127
	v_mov_b32_e32 v36, v127
	v_mov_b32_e32 v35, v127
	v_mov_b32_e32 v34, v127
	v_mov_b32_e32 v33, v127
	v_mov_b32_e32 v32, v127
	v_mov_b32_e32 v31, v127
	v_mov_b32_e32 v30, v127
	v_mov_b32_e32 v29, v127
	v_mov_b32_e32 v28, v127
	v_mov_b32_e32 v27, v127
	v_mov_b32_e32 v26, v127
	v_mov_b32_e32 v25, v127
	v_mov_b32_e32 v24, v127
	v_mov_b32_e32 v23, v127
	v_mov_b32_e32 v22, v127
	v_mov_b32_e32 v21, v127
	v_mov_b32_e32 v20, v127
	v_mov_b32_e32 v19, v127
	v_mov_b32_e32 v18, v127
	v_mov_b32_e32 v17, v127
	v_mov_b32_e32 v16, v127
	v_mov_b32_e32 v15, v127
	v_mov_b32_e32 v14, v127
	v_mov_b32_e32 v13, v127
	v_mov_b32_e32 v12, v127
	v_mov_b32_e32 v11, v127
	v_mov_b32_e32 v10, v127
	v_mov_b32_e32 v9, v127
	v_mov_b32_e32 v8, v127
	v_mov_b32_e32 v7, v127
	v_mov_b32_e32 v6, v127
	v_mov_b32_e32 v5, v127
	v_mov_b32_e32 v4, v127
	v_mov_b32_e32 v3, v127
	v_mov_b32_e32 v2, v127
	v_mov_b32_e32 v1, v127
	v_mov_b32_e32 v0, v127
	s_barrier
	s_cbranch_scc1 .LBB0_1328
	s_ashr_i32 s59, s58, 31
	s_ashr_i32 s5, s4, 31
	v_readlane_b32 s60, v254, 54
	s_add_i32 s0, s48, -2
	s_lshl_b64 s[50:51], s[58:59], 11
	s_lshl_b64 s[52:53], s[4:5], 11
	v_readlane_b32 s62, v254, 56
	v_readlane_b32 s61, v254, 55
	v_readlane_b32 s63, v254, 57
	v_readlane_b32 s64, v254, 58
	v_readlane_b32 s65, v254, 59
	v_readlane_b32 s66, v254, 60
	v_readlane_b32 s67, v254, 61
	v_readlane_b32 s68, v254, 62
	v_readlane_b32 s69, v254, 63
	v_readlane_b32 s70, v255, 0
	v_readlane_b32 s71, v255, 1
	v_readlane_b32 s72, v255, 2
	v_readlane_b32 s73, v255, 3
	v_readlane_b32 s74, v255, 4
	v_readlane_b32 s75, v255, 5
	s_add_u32 s50, s62, s50
	s_addc_u32 s51, s63, s51
	v_readlane_b32 s60, v255, 10
	v_readlane_b32 s64, v255, 14
	v_readlane_b32 s65, v255, 15
	s_add_u32 s52, s64, s52
	v_mov_b32_e32 v0, 0
	s_addc_u32 s53, s65, s53
	s_mov_b32 s1, 0
	v_readlane_b32 s61, v255, 11
	v_readlane_b32 s62, v255, 12
	v_readlane_b32 s63, v255, 13
	v_readlane_b32 s66, v255, 16
	v_readlane_b32 s67, v255, 17
	v_readlane_b32 s68, v255, 18
	v_readlane_b32 s69, v255, 19
	v_readlane_b32 s70, v255, 20
	v_readlane_b32 s71, v255, 21
	v_readlane_b32 s72, v255, 22
	v_readlane_b32 s73, v255, 23
	v_readlane_b32 s74, v255, 24
	v_readlane_b32 s75, v255, 25

; #define WAIT_V(n) asm volatile("s_waitcnt vmcnt(" #n ")" ::: "memory")
; #define BAR __builtin_amdgcn_s_barrier()
; template <class Epi>
; __device__ __forceinline__ void gemm_phase(const bfr* __restrict__ A, int lda, const bfr* __restrict__ Bt, int K,
;                                            int nM, int nN, const Epi& epi, bfr* shm, int wv, int nMfull, int ksplit) {
;     ...
;     const bfr* Ak = A + kbeg; const bfr* Bk = Bt + kbeg;
;     f32x4 acc[2][2][4][2];
; #pragma unroll
;     for (int a = 0; a < 2; a++)
; #pragma unroll
;       for (int b = 0; b < 2; b++)
; #pragma unroll
;         for (int m = 0; m < 4; m++)
; #pragma unroll
;           for (int n = 0; n < 2; n++) acc[a][b][m][n] = f32x4{0.f, 0.f, 0.f, 0.f};
;     bf16x8 At[4][2], B0[2][2], B1[2][2];
;     if (wr == 1) BAR;
;     WAIT_V(10); BAR;
;     WAIT_V(6); BAR;
;     for (int t = 0; t < nt - 2; t += 2) {
.LBB0_1366:
	s_waitcnt vmcnt(10)
	s_barrier
	s_waitcnt vmcnt(6)
	v_mov_b32_e32 v127, 0
	s_cmp_lt_u32 s56, 3
	v_mov_b32_e32 v126, v127
	v_mov_b32_e32 v125, v127
	v_mov_b32_e32 v124, v127
	v_mov_b32_e32 v123, v127
	v_mov_b32_e32 v122, v127
	v_mov_b32_e32 v121, v127
	v_mov_b32_e32 v120, v127
	v_mov_b32_e32 v119, v127
	v_mov_b32_e32 v118, v127
	v_mov_b32_e32 v117, v127
	v_mov_b32_e32 v116, v127
	v_mov_b32_e32 v115, v127
	v_mov_b32_e32 v114, v127
	v_mov_b32_e32 v113, v127
	v_mov_b32_e32 v112, v127
	v_mov_b32_e32 v111, v127
	v_mov_b32_e32 v110, v127
	v_mov_b32_e32 v109, v127
	v_mov_b32_e32 v108, v127
	v_mov_b32_e32 v107, v127
	v_mov_b32_e32 v106, v127
	v_mov_b32_e32 v105, v127
	v_mov_b32_e32 v104, v127
	v_mov_b32_e32 v103, v127
	v_mov_b32_e32 v102, v127
	v_mov_b32_e32 v101, v127
	v_mov_b32_e32 v100, v127
	v_mov_b32_e32 v99, v127
	v_mov_b32_e32 v98, v127
	v_mov_b32_e32 v97, v127
	v_mov_b32_e32 v96, v127
	v_mov_b32_e32 v95, v127
	v_mov_b32_e32 v94, v127
	v_mov_b32_e32 v93, v127
	v_mov_b32_e32 v92, v127
	v_mov_b32_e32 v91, v127
	v_mov_b32_e32 v90, v127
	v_mov_b32_e32 v89, v127
	v_mov_b32_e32 v88, v127
	v_mov_b32_e32 v87, v127
	v_mov_b32_e32 v86, v127
	v_mov_b32_e32 v85, v127
	v_mov_b32_e32 v84, v127
	v_mov_b32_e32 v83, v127
	v_mov_b32_e32 v82, v127
	v_mov_b32_e32 v81, v127
	v_mov_b32_e32 v80, v127
	v_mov_b32_e32 v79, v127
	v_mov_b32_e32 v78, v127
	v_mov_b32_e32 v77, v127
	v_mov_b32_e32 v76, v127
	v_mov_b32_e32 v75, v127
	v_mov_b32_e32 v74, v127
	v_mov_b32_e32 v73, v127
	v_mov_b32_e32 v72, v127
	v_mov_b32_e32 v71, v127
	v_mov_b32_e32 v70, v127
	v_mov_b32_e32 v69, v127
	v_mov_b32_e32 v68, v127
	v_mov_b32_e32 v67, v127
	v_mov_b32_e32 v66, v127
	v_mov_b32_e32 v65, v127
	v_mov_b32_e32 v64, v127
	v_mov_b32_e32 v63, v127
	v_mov_b32_e32 v62, v127
	v_mov_b32_e32 v61, v127
	v_mov_b32_e32 v60, v127
	v_mov_b32_e32 v59, v127
	v_mov_b32_e32 v58, v127
	v_mov_b32_e32 v57, v127
	v_mov_b32_e32 v56, v127
	v_mov_b32_e32 v55, v127
	v_mov_b32_e32 v54, v127
	v_mov_b32_e32 v53, v127
	v_mov_b32_e32 v52, v127
	v_mov_b32_e32 v51, v127
	v_mov_b32_e32 v50, v127
	v_mov_b32_e32 v49, v127
	v_mov_b32_e32 v48, v127
	v_mov_b32_e32 v47, v127
	v_mov_b32_e32 v46, v127
	v_mov_b32_e32 v45, v127
	v_mov_b32_e32 v44, v127
	v_mov_b32_e32 v43, v127
	v_mov_b32_e32 v42, v127
	v_mov_b32_e32 v41, v127
	v_mov_b32_e32 v40, v127
	v_mov_b32_e32 v39, v127
	v_mov_b32_e32 v38, v127
	v_mov_b32_e32 v37, v127
	v_mov_b32_e32 v36, v127
	v_mov_b32_e32 v35, v127
	v_mov_b32_e32 v34, v127
	v_mov_b32_e32 v33, v127
	v_mov_b32_e32 v32, v127
	v_mov_b32_e32 v31, v127
	v_mov_b32_e32 v30, v127
	v_mov_b32_e32 v29, v127
	v_mov_b32_e32 v28, v127
	v_mov_b32_e32 v27, v127
	v_mov_b32_e32 v26, v127
	v_mov_b32_e32 v25, v127
	v_mov_b32_e32 v24, v127
	v_mov_b32_e32 v23, v127
	v_mov_b32_e32 v22, v127
	v_mov_b32_e32 v21, v127
	v_mov_b32_e32 v20, v127
	v_mov_b32_e32 v19, v127
	v_mov_b32_e32 v18, v127
	v_mov_b32_e32 v17, v127
	v_mov_b32_e32 v16, v127
	v_mov_b32_e32 v15, v127
	v_mov_b32_e32 v14, v127
	v_mov_b32_e32 v13, v127
	v_mov_b32_e32 v12, v127
	v_mov_b32_e32 v11, v127
	v_mov_b32_e32 v10, v127
	v_mov_b32_e32 v9, v127
	v_mov_b32_e32 v8, v127
	v_mov_b32_e32 v7, v127
	v_mov_b32_e32 v6, v127
	v_mov_b32_e32 v5, v127
	v_mov_b32_e32 v4, v127
	v_mov_b32_e32 v3, v127
	v_mov_b32_e32 v2, v127
	v_mov_b32_e32 v1, v127
	v_mov_b32_e32 v0, v127
	s_barrier
	s_cbranch_scc1 .LBB0_1369
	s_mul_i32 s60, s58, 0xb00
	s_ashr_i32 s61, s60, 31
	v_readlane_b32 s76, v254, 54
	s_add_i32 s57, s56, -2
	s_lshl_b64 s[60:61], s[60:61], 1
	v_readlane_b32 s80, v254, 58
	v_readlane_b32 s77, v254, 55
	v_readlane_b32 s78, v254, 56
	v_readlane_b32 s79, v254, 57
	v_readlane_b32 s81, v254, 59
	v_readlane_b32 s82, v254, 60
	v_readlane_b32 s83, v254, 61
	v_readlane_b32 s84, v254, 62
	v_readlane_b32 s85, v254, 63
	v_readlane_b32 s86, v255, 0
	v_readlane_b32 s87, v255, 1
	v_readlane_b32 s88, v255, 2
	v_readlane_b32 s89, v255, 3
	v_readlane_b32 s90, v255, 4
	v_readlane_b32 s91, v255, 5
	s_add_u32 s60, s80, s60
	s_addc_u32 s61, s81, s61
	v_readlane_b32 s76, v255, 10
	s_mul_i32 s64, s94, 0x1600
	v_readlane_b32 s82, v255, 16
	s_mul_hi_i32 s59, s94, 0x1600
	v_readlane_b32 s83, v255, 17
	s_add_u32 s64, s82, s64
	v_mov_b32_e32 v0, 0
	s_addc_u32 s65, s83, s59
	s_mov_b32 s59, 0
	v_readlane_b32 s77, v255, 11
	v_readlane_b32 s78, v255, 12
	v_readlane_b32 s79, v255, 13
	v_readlane_b32 s80, v255, 14
	v_readlane_b32 s81, v255, 15
	v_readlane_b32 s84, v255, 18
	v_readlane_b32 s85, v255, 19
	v_readlane_b32 s86, v255, 20
	v_readlane_b32 s87, v255, 21
	v_readlane_b32 s88, v255, 22
	v_readlane_b32 s89, v255, 23
	v_readlane_b32 s90, v255, 24
	v_readlane_b32 s91, v255, 25
